# coop K/V chunk loads + PV read pipelining in diff pass B; hoisted serialized g_diff loads in diff epilogues; hoisted row-stat loads in P1/P5 epilogues
# speedup vs baseline: 1.0049x; 1.0049x over previous
; __device__ __forceinline__ unsigned cvt_pk_bf16(float lo, float hi) { unsigned r; asm volatile("v_cvt_pk_bf16_f32 %0, %1, %2" : "=v"(r) : "v"(lo), "v"(hi)); return r; }
;     __device__ __forceinline__ void operator()(f32x4 (&acc)[2][2][4][2], const Unit& u, int wr, int wc, int fr, int fq) const {
;         const int row0 = u.orow + wr * 64 + fr, col0 = u.ocol + wc * 32 + 8 * fq;
;         f32x4 cv[2][2], bv[2][2];
; #pragma unroll
;         for (int bj = 0; bj < 2; ++bj)
; #pragma unroll
;             for (int n = 0; n < 2; ++n) { cv[bj][n] = *(const f32x4*)(cs + col0 + bj * HALF + 4 * n); bv[bj][n] = *(const f32x4*)(bw + col0 + bj * HALF + 4 * n); }
; #pragma unroll
;         for (int ai = 0; ai < 2; ++ai)
; #pragma unroll
;             for (int m = 0; m < 4; ++m) { const int row = row0 + ai * HALF + m * 16; bf16_t* rowp = O + (size_t)row * ldc + col0;
;                 const f32x2 st = *(const f32x2*)(ps + (size_t)row * 2); const float rs = st[1], nm = -st[0] * rs;
; #pragma unroll
;                 for (int bj = 0; bj < 2; ++bj) { const f32x4 v0 = acc[ai][bj][m][0] * rs + (cv[bj][0] * nm + bv[bj][0]), v1 = acc[ai][bj][m][1] * rs + (cv[bj][1] * nm + bv[bj][1]);
;                     u32x4 w; w.x = cvt_pk_bf16(v0[0], v0[1]); w.y = cvt_pk_bf16(v0[2], v0[3]); w.z = cvt_pk_bf16(v1[0], v1[1]); w.w = cvt_pk_bf16(v1[2], v1[3]);
;                     *(u32x4*)(rowp + bj * HALF) = w; } }
.LBB0_255:
	v_add_u32_e32 v164, s1, v172
	v_ashrrev_i32_e32 v165, 31, v164
	v_readlane_b32 s2, v249, 46
	v_add_u32_e32 v166, s0, v171
	v_lshlrev_b64 v[50:51], 2, v[164:165]
	v_readlane_b32 s3, v249, 47
	v_ashrrev_i32_e32 v167, 31, v166
	v_lshl_add_u64 v[58:59], s[64:65], 0, v[50:51]
	v_lshl_add_u64 v[74:75], s[2:3], 0, v[50:51]
	v_lshl_add_u64 v[184:185], v[166:167], 3, s[70:71]
	global_load_dwordx4 v[54:57], v[58:59], off offset:16
	global_load_dwordx4 v[70:73], v[58:59], off
	global_load_dwordx4 v[62:65], v[74:75], off offset:16
	global_load_dwordx4 v[78:81], v[74:75], off
	global_load_dwordx4 v[50:53], v[58:59], off offset:528
	global_load_dwordx4 v[66:69], v[58:59], off offset:512
	s_nop 0
	global_load_dwordx4 v[58:61], v[74:75], off offset:528
	s_nop 0
	global_load_dwordx4 v[74:77], v[74:75], off offset:512
	v_mov_b64_e32 v[162:163], s[74:75]
	global_load_dwordx2 v[230:231], v[184:185], off offset:128
	global_load_dwordx2 v[232:233], v[184:185], off offset:256
	global_load_dwordx2 v[234:235], v[184:185], off offset:384
	global_load_dwordx2 v[236:237], v[184:185], off offset:1024
	global_load_dwordx2 v[238:239], v[184:185], off offset:1152
	global_load_dwordx2 v[240:241], v[184:185], off offset:1280
	global_load_dwordx2 v[196:197], v[184:185], off offset:1408
	global_load_dwordx2 v[184:185], v[184:185], off
	s_movk_i32 s2, 0x3000
	v_mad_i64_i32 v[176:177], s[0:1], v166, s2, v[162:163]
	v_lshlrev_b64 v[164:165], 1, v[164:165]
	v_lshl_add_u64 v[176:177], v[176:177], 0, v[164:165]
	s_andn2_b64 vcc, exec, s[38:39]
	s_waitcnt vmcnt(0)
	v_mul_f32_e64 v178, v185, -v184
	v_pk_fma_f32 v[186:187], v[72:73], v[178:179], v[80:81] op_sel_hi:[1, 0, 1]
	v_pk_fma_f32 v[194:195], v[70:71], v[178:179], v[78:79] op_sel_hi:[1, 0, 1]
	v_pk_fma_f32 v[160:161], v[160:161], v[184:185], v[186:187] op_sel:[0, 1, 0]
	v_pk_fma_f32 v[158:159], v[158:159], v[184:185], v[194:195] op_sel:[0, 1, 0]
	v_pk_fma_f32 v[186:187], v[56:57], v[178:179], v[64:65] op_sel_hi:[1, 0, 1]
	v_pk_fma_f32 v[194:195], v[54:55], v[178:179], v[62:63] op_sel_hi:[1, 0, 1]
	v_pk_fma_f32 v[186:187], v[156:157], v[184:185], v[186:187] op_sel:[0, 1, 0]
	v_pk_fma_f32 v[156:157], v[154:155], v[184:185], v[194:195] op_sel:[0, 1, 0]
	v_cvt_pk_bf16_f32 v154, v158, v159
	v_cvt_pk_bf16_f32 v155, v160, v161
	s_nop 0
	v_cvt_pk_bf16_f32 v156, v156, v157
	v_cvt_pk_bf16_f32 v157, v186, v187
	global_store_dwordx4 v[176:177], v[154:157], off
	s_nop 1
	v_pk_fma_f32 v[154:155], v[68:69], v[178:179], v[76:77] op_sel_hi:[1, 0, 1]
	v_pk_fma_f32 v[156:157], v[66:67], v[178:179], v[74:75] op_sel_hi:[1, 0, 1]
	v_pk_fma_f32 v[152:153], v[152:153], v[184:185], v[154:155] op_sel:[0, 1, 0]
	v_pk_fma_f32 v[150:151], v[150:151], v[184:185], v[156:157] op_sel:[0, 1, 0]
	v_pk_fma_f32 v[154:155], v[52:53], v[178:179], v[60:61] op_sel_hi:[1, 0, 1]
	v_pk_fma_f32 v[156:157], v[50:51], v[178:179], v[58:59] op_sel_hi:[1, 0, 1]
	v_pk_fma_f32 v[154:155], v[148:149], v[184:185], v[154:155] op_sel:[0, 1, 0]
	v_pk_fma_f32 v[148:149], v[146:147], v[184:185], v[156:157] op_sel:[0, 1, 0]
	v_cvt_pk_bf16_f32 v146, v150, v151
	v_cvt_pk_bf16_f32 v147, v152, v153
	s_nop 0
	v_cvt_pk_bf16_f32 v148, v148, v149
	v_cvt_pk_bf16_f32 v149, v154, v155
	global_store_dwordx4 v[176:177], v[146:149], off offset:256
	s_nop 1
	v_add_u32_e32 v146, 16, v166
	v_ashrrev_i32_e32 v147, 31, v146
	v_mad_i64_i32 v[148:149], s[0:1], v146, s2, v[162:163]
	v_lshl_add_u64 v[148:149], v[148:149], 0, v[164:165]
	v_mul_f32_e64 v150, v231, -v230
	v_pk_fma_f32 v[152:153], v[72:73], v[150:151], v[80:81] op_sel_hi:[1, 0, 1]
	v_pk_fma_f32 v[154:155], v[70:71], v[150:151], v[78:79] op_sel_hi:[1, 0, 1]
	v_pk_fma_f32 v[144:145], v[144:145], v[230:231], v[152:153] op_sel:[0, 1, 0]
	v_pk_fma_f32 v[142:143], v[142:143], v[230:231], v[154:155] op_sel:[0, 1, 0]
	v_pk_fma_f32 v[152:153], v[56:57], v[150:151], v[64:65] op_sel_hi:[1, 0, 1]
	v_pk_fma_f32 v[154:155], v[54:55], v[150:151], v[62:63] op_sel_hi:[1, 0, 1]
	v_pk_fma_f32 v[152:153], v[140:141], v[230:231], v[152:153] op_sel:[0, 1, 0]
	v_pk_fma_f32 v[140:141], v[138:139], v[230:231], v[154:155] op_sel:[0, 1, 0]
	v_cvt_pk_bf16_f32 v138, v142, v143
	v_cvt_pk_bf16_f32 v139, v144, v145
	s_nop 0
	v_cvt_pk_bf16_f32 v140, v140, v141
	v_cvt_pk_bf16_f32 v141, v152, v153
	global_store_dwordx4 v[148:149], v[138:141], off
	s_nop 1
	v_pk_fma_f32 v[138:139], v[68:69], v[150:151], v[76:77] op_sel_hi:[1, 0, 1]
	v_pk_fma_f32 v[140:141], v[66:67], v[150:151], v[74:75] op_sel_hi:[1, 0, 1]
	v_pk_fma_f32 v[136:137], v[136:137], v[230:231], v[138:139] op_sel:[0, 1, 0]
	v_pk_fma_f32 v[134:135], v[134:135], v[230:231], v[140:141] op_sel:[0, 1, 0]
	v_pk_fma_f32 v[138:139], v[52:53], v[150:151], v[60:61] op_sel_hi:[1, 0, 1]
	v_pk_fma_f32 v[140:141], v[50:51], v[150:151], v[58:59] op_sel_hi:[1, 0, 1]
	v_pk_fma_f32 v[138:139], v[132:133], v[230:231], v[138:139] op_sel:[0, 1, 0]
	v_pk_fma_f32 v[132:133], v[130:131], v[230:231], v[140:141] op_sel:[0, 1, 0]
	v_cvt_pk_bf16_f32 v130, v134, v135
	v_cvt_pk_bf16_f32 v131, v136, v137
	s_nop 0
	v_cvt_pk_bf16_f32 v132, v132, v133
	v_cvt_pk_bf16_f32 v133, v138, v139
	global_store_dwordx4 v[148:149], v[130:133], off offset:256
	s_nop 1
	v_add_u32_e32 v130, 32, v166
	v_ashrrev_i32_e32 v131, 31, v130
	v_mad_i64_i32 v[132:133], s[0:1], v130, s2, v[162:163]
	v_lshl_add_u64 v[132:133], v[132:133], 0, v[164:165]
	v_mul_f32_e64 v134, v233, -v232
	v_pk_fma_f32 v[136:137], v[72:73], v[134:135], v[80:81] op_sel_hi:[1, 0, 1]
	v_pk_fma_f32 v[138:139], v[70:71], v[134:135], v[78:79] op_sel_hi:[1, 0, 1]
	v_pk_fma_f32 v[128:129], v[128:129], v[232:233], v[136:137] op_sel:[0, 1, 0]
	v_pk_fma_f32 v[126:127], v[126:127], v[232:233], v[138:139] op_sel:[0, 1, 0]
; __device__ __forceinline__ unsigned cvt_pk_bf16(float lo, float hi) { unsigned r; asm volatile("v_cvt_pk_bf16_f32 %0, %1, %2" : "=v"(r) : "v"(lo), "v"(hi)); return r; }
;     __device__ __forceinline__ void operator()(f32x4 (&acc)[2][2][4][2], const Unit& u, int wr, int wc, int fr, int fq) const {
;     ...
;             for (int m = 0; m < 4; ++m) { const int row = row0 + ai * HALF + m * 16; bf16_t* rowp = O + (size_t)row * ldc + col0;
;                 const f32x2 st = *(const f32x2*)(ps + (size_t)row * 2); const float rs = st[1], nm = -st[0] * rs;
; #pragma unroll
;                 for (int bj = 0; bj < 2; ++bj) { const f32x4 v0 = acc[ai][bj][m][0] * rs + (cv[bj][0] * nm + bv[bj][0]), v1 = acc[ai][bj][m][1] * rs + (cv[bj][1] * nm + bv[bj][1]);
;                     u32x4 w; w.x = cvt_pk_bf16(v0[0], v0[1]); w.y = cvt_pk_bf16(v0[2], v0[3]); w.z = cvt_pk_bf16(v1[0], v1[1]); w.w = cvt_pk_bf16(v1[2], v1[3]);
;                     *(u32x4*)(rowp + bj * HALF) = w; } }
	v_pk_fma_f32 v[136:137], v[56:57], v[134:135], v[64:65] op_sel_hi:[1, 0, 1]
	v_pk_fma_f32 v[138:139], v[54:55], v[134:135], v[62:63] op_sel_hi:[1, 0, 1]
	v_pk_fma_f32 v[136:137], v[124:125], v[232:233], v[136:137] op_sel:[0, 1, 0]
	v_pk_fma_f32 v[124:125], v[122:123], v[232:233], v[138:139] op_sel:[0, 1, 0]
	v_cvt_pk_bf16_f32 v122, v126, v127
	v_cvt_pk_bf16_f32 v123, v128, v129
	s_nop 0
	v_cvt_pk_bf16_f32 v124, v124, v125
	v_cvt_pk_bf16_f32 v125, v136, v137
	global_store_dwordx4 v[132:133], v[122:125], off
	s_nop 1
	v_pk_fma_f32 v[122:123], v[68:69], v[134:135], v[76:77] op_sel_hi:[1, 0, 1]
	v_pk_fma_f32 v[124:125], v[66:67], v[134:135], v[74:75] op_sel_hi:[1, 0, 1]
	v_pk_fma_f32 v[120:121], v[120:121], v[232:233], v[122:123] op_sel:[0, 1, 0]
	v_pk_fma_f32 v[118:119], v[118:119], v[232:233], v[124:125] op_sel:[0, 1, 0]
	v_pk_fma_f32 v[122:123], v[52:53], v[134:135], v[60:61] op_sel_hi:[1, 0, 1]
	v_pk_fma_f32 v[124:125], v[50:51], v[134:135], v[58:59] op_sel_hi:[1, 0, 1]
	v_pk_fma_f32 v[122:123], v[116:117], v[232:233], v[122:123] op_sel:[0, 1, 0]
	v_pk_fma_f32 v[116:117], v[114:115], v[232:233], v[124:125] op_sel:[0, 1, 0]
	v_cvt_pk_bf16_f32 v114, v118, v119
	v_cvt_pk_bf16_f32 v115, v120, v121
	s_nop 0
	v_cvt_pk_bf16_f32 v116, v116, v117
	v_cvt_pk_bf16_f32 v117, v122, v123
	global_store_dwordx4 v[132:133], v[114:117], off offset:256
	s_nop 1
	v_add_u32_e32 v114, 48, v166
	v_ashrrev_i32_e32 v115, 31, v114
	v_mad_i64_i32 v[116:117], s[0:1], v114, s2, v[162:163]
	v_lshl_add_u64 v[116:117], v[116:117], 0, v[164:165]
	v_mul_f32_e64 v118, v235, -v234
	v_pk_fma_f32 v[120:121], v[72:73], v[118:119], v[80:81] op_sel_hi:[1, 0, 1]
	v_pk_fma_f32 v[122:123], v[70:71], v[118:119], v[78:79] op_sel_hi:[1, 0, 1]
	v_pk_fma_f32 v[112:113], v[112:113], v[234:235], v[120:121] op_sel:[0, 1, 0]
	v_pk_fma_f32 v[110:111], v[110:111], v[234:235], v[122:123] op_sel:[0, 1, 0]
	v_pk_fma_f32 v[120:121], v[56:57], v[118:119], v[64:65] op_sel_hi:[1, 0, 1]
	v_pk_fma_f32 v[122:123], v[54:55], v[118:119], v[62:63] op_sel_hi:[1, 0, 1]
	v_pk_fma_f32 v[120:121], v[108:109], v[234:235], v[120:121] op_sel:[0, 1, 0]
	v_pk_fma_f32 v[108:109], v[106:107], v[234:235], v[122:123] op_sel:[0, 1, 0]
	v_cvt_pk_bf16_f32 v106, v110, v111
	v_cvt_pk_bf16_f32 v107, v112, v113
	s_nop 0
	v_cvt_pk_bf16_f32 v108, v108, v109
	v_cvt_pk_bf16_f32 v109, v120, v121
	global_store_dwordx4 v[116:117], v[106:109], off
	s_nop 1
	v_pk_fma_f32 v[106:107], v[68:69], v[118:119], v[76:77] op_sel_hi:[1, 0, 1]
	v_pk_fma_f32 v[108:109], v[66:67], v[118:119], v[74:75] op_sel_hi:[1, 0, 1]
	v_pk_fma_f32 v[104:105], v[104:105], v[234:235], v[106:107] op_sel:[0, 1, 0]
	v_pk_fma_f32 v[102:103], v[102:103], v[234:235], v[108:109] op_sel:[0, 1, 0]
	v_pk_fma_f32 v[106:107], v[52:53], v[118:119], v[60:61] op_sel_hi:[1, 0, 1]
	v_pk_fma_f32 v[108:109], v[50:51], v[118:119], v[58:59] op_sel_hi:[1, 0, 1]
	v_pk_fma_f32 v[106:107], v[100:101], v[234:235], v[106:107] op_sel:[0, 1, 0]
	v_pk_fma_f32 v[100:101], v[98:99], v[234:235], v[108:109] op_sel:[0, 1, 0]
	v_cvt_pk_bf16_f32 v98, v102, v103
	v_cvt_pk_bf16_f32 v99, v104, v105
	s_nop 0
	v_cvt_pk_bf16_f32 v100, v100, v101
	v_cvt_pk_bf16_f32 v101, v106, v107
	global_store_dwordx4 v[116:117], v[98:101], off offset:256
	s_nop 1
	v_add_u32_e32 v98, 0x80, v166
	v_ashrrev_i32_e32 v99, 31, v98
	v_mad_i64_i32 v[100:101], s[0:1], v98, s2, v[162:163]
	v_lshl_add_u64 v[100:101], v[100:101], 0, v[164:165]
	v_mul_f32_e64 v102, v237, -v236
	v_pk_fma_f32 v[104:105], v[72:73], v[102:103], v[80:81] op_sel_hi:[1, 0, 1]
	v_pk_fma_f32 v[106:107], v[70:71], v[102:103], v[78:79] op_sel_hi:[1, 0, 1]
	v_pk_fma_f32 v[96:97], v[96:97], v[236:237], v[104:105] op_sel:[0, 1, 0]
	v_pk_fma_f32 v[94:95], v[94:95], v[236:237], v[106:107] op_sel:[0, 1, 0]
	v_pk_fma_f32 v[104:105], v[56:57], v[102:103], v[64:65] op_sel_hi:[1, 0, 1]
	v_pk_fma_f32 v[106:107], v[54:55], v[102:103], v[62:63] op_sel_hi:[1, 0, 1]
	v_pk_fma_f32 v[104:105], v[92:93], v[236:237], v[104:105] op_sel:[0, 1, 0]
	v_pk_fma_f32 v[92:93], v[90:91], v[236:237], v[106:107] op_sel:[0, 1, 0]
	v_cvt_pk_bf16_f32 v90, v94, v95
	v_cvt_pk_bf16_f32 v91, v96, v97
	s_nop 0
	v_cvt_pk_bf16_f32 v92, v92, v93
	v_cvt_pk_bf16_f32 v93, v104, v105
	global_store_dwordx4 v[100:101], v[90:93], off
	s_nop 1
	v_pk_fma_f32 v[90:91], v[68:69], v[102:103], v[76:77] op_sel_hi:[1, 0, 1]
	v_pk_fma_f32 v[92:93], v[66:67], v[102:103], v[74:75] op_sel_hi:[1, 0, 1]
	v_pk_fma_f32 v[88:89], v[88:89], v[236:237], v[90:91] op_sel:[0, 1, 0]
	v_pk_fma_f32 v[86:87], v[86:87], v[236:237], v[92:93] op_sel:[0, 1, 0]
	v_pk_fma_f32 v[90:91], v[52:53], v[102:103], v[60:61] op_sel_hi:[1, 0, 1]
	v_pk_fma_f32 v[92:93], v[50:51], v[102:103], v[58:59] op_sel_hi:[1, 0, 1]
	v_pk_fma_f32 v[90:91], v[84:85], v[236:237], v[90:91] op_sel:[0, 1, 0]
	v_pk_fma_f32 v[84:85], v[82:83], v[236:237], v[92:93] op_sel:[0, 1, 0]
	v_cvt_pk_bf16_f32 v82, v86, v87
	v_cvt_pk_bf16_f32 v83, v88, v89
	s_nop 0
	v_cvt_pk_bf16_f32 v84, v84, v85
	v_cvt_pk_bf16_f32 v85, v90, v91
	global_store_dwordx4 v[100:101], v[82:85], off offset:256
	s_nop 1
	v_add_u32_e32 v82, 0x90, v166
	v_ashrrev_i32_e32 v83, 31, v82
	v_mad_i64_i32 v[84:85], s[0:1], v82, s2, v[162:163]
	v_lshl_add_u64 v[84:85], v[84:85], 0, v[164:165]
; __device__ __forceinline__ unsigned cvt_pk_bf16(float lo, float hi) { unsigned r; asm volatile("v_cvt_pk_bf16_f32 %0, %1, %2" : "=v"(r) : "v"(lo), "v"(hi)); return r; }
;     __device__ __forceinline__ void operator()(f32x4 (&acc)[2][2][4][2], const Unit& u, int wr, int wc, int fr, int fq) const {
;     ...
;             for (int m = 0; m < 4; ++m) { const int row = row0 + ai * HALF + m * 16; bf16_t* rowp = O + (size_t)row * ldc + col0;
;                 const f32x2 st = *(const f32x2*)(ps + (size_t)row * 2); const float rs = st[1], nm = -st[0] * rs;
; #pragma unroll
;                 for (int bj = 0; bj < 2; ++bj) { const f32x4 v0 = acc[ai][bj][m][0] * rs + (cv[bj][0] * nm + bv[bj][0]), v1 = acc[ai][bj][m][1] * rs + (cv[bj][1] * nm + bv[bj][1]);
;                     u32x4 w; w.x = cvt_pk_bf16(v0[0], v0[1]); w.y = cvt_pk_bf16(v0[2], v0[3]); w.z = cvt_pk_bf16(v1[0], v1[1]); w.w = cvt_pk_bf16(v1[2], v1[3]);
;                     *(u32x4*)(rowp + bj * HALF) = w; } }
	v_mul_f32_e64 v86, v239, -v238
	v_pk_fma_f32 v[88:89], v[72:73], v[86:87], v[80:81] op_sel_hi:[1, 0, 1]
	v_pk_fma_f32 v[90:91], v[70:71], v[86:87], v[78:79] op_sel_hi:[1, 0, 1]
	v_pk_fma_f32 v[48:49], v[48:49], v[238:239], v[88:89] op_sel:[0, 1, 0]
	v_pk_fma_f32 v[46:47], v[46:47], v[238:239], v[90:91] op_sel:[0, 1, 0]
	v_pk_fma_f32 v[88:89], v[56:57], v[86:87], v[64:65] op_sel_hi:[1, 0, 1]
	v_pk_fma_f32 v[90:91], v[54:55], v[86:87], v[62:63] op_sel_hi:[1, 0, 1]
	v_pk_fma_f32 v[88:89], v[44:45], v[238:239], v[88:89] op_sel:[0, 1, 0]
	v_pk_fma_f32 v[44:45], v[42:43], v[238:239], v[90:91] op_sel:[0, 1, 0]
	v_cvt_pk_bf16_f32 v42, v46, v47
	v_cvt_pk_bf16_f32 v43, v48, v49
	s_nop 0
	v_cvt_pk_bf16_f32 v44, v44, v45
	v_cvt_pk_bf16_f32 v45, v88, v89
	global_store_dwordx4 v[84:85], v[42:45], off
	s_nop 1
	v_pk_fma_f32 v[42:43], v[68:69], v[86:87], v[76:77] op_sel_hi:[1, 0, 1]
	v_pk_fma_f32 v[44:45], v[66:67], v[86:87], v[74:75] op_sel_hi:[1, 0, 1]
	v_pk_fma_f32 v[40:41], v[40:41], v[238:239], v[42:43] op_sel:[0, 1, 0]
	v_pk_fma_f32 v[38:39], v[38:39], v[238:239], v[44:45] op_sel:[0, 1, 0]
	v_pk_fma_f32 v[42:43], v[52:53], v[86:87], v[60:61] op_sel_hi:[1, 0, 1]
	v_pk_fma_f32 v[44:45], v[50:51], v[86:87], v[58:59] op_sel_hi:[1, 0, 1]
	v_pk_fma_f32 v[42:43], v[36:37], v[238:239], v[42:43] op_sel:[0, 1, 0]
	v_pk_fma_f32 v[36:37], v[34:35], v[238:239], v[44:45] op_sel:[0, 1, 0]
	v_cvt_pk_bf16_f32 v34, v38, v39
	v_cvt_pk_bf16_f32 v35, v40, v41
	s_nop 0
	v_cvt_pk_bf16_f32 v36, v36, v37
	v_cvt_pk_bf16_f32 v37, v42, v43
	global_store_dwordx4 v[84:85], v[34:37], off offset:256
	s_nop 1
	v_add_u32_e32 v34, 0xa0, v166
	v_ashrrev_i32_e32 v35, 31, v34
	v_mad_i64_i32 v[36:37], s[0:1], v34, s2, v[162:163]
	v_lshl_add_u64 v[36:37], v[36:37], 0, v[164:165]
	v_mul_f32_e64 v38, v241, -v240
	v_pk_fma_f32 v[40:41], v[72:73], v[38:39], v[80:81] op_sel_hi:[1, 0, 1]
	v_pk_fma_f32 v[42:43], v[70:71], v[38:39], v[78:79] op_sel_hi:[1, 0, 1]
	v_pk_fma_f32 v[32:33], v[32:33], v[240:241], v[40:41] op_sel:[0, 1, 0]
	v_pk_fma_f32 v[30:31], v[30:31], v[240:241], v[42:43] op_sel:[0, 1, 0]
	v_pk_fma_f32 v[40:41], v[56:57], v[38:39], v[64:65] op_sel_hi:[1, 0, 1]
	v_pk_fma_f32 v[42:43], v[54:55], v[38:39], v[62:63] op_sel_hi:[1, 0, 1]
	v_pk_fma_f32 v[40:41], v[28:29], v[240:241], v[40:41] op_sel:[0, 1, 0]
	v_pk_fma_f32 v[28:29], v[26:27], v[240:241], v[42:43] op_sel:[0, 1, 0]
	v_cvt_pk_bf16_f32 v26, v30, v31
	v_cvt_pk_bf16_f32 v27, v32, v33
	s_nop 0
	v_cvt_pk_bf16_f32 v28, v28, v29
	v_cvt_pk_bf16_f32 v29, v40, v41
	global_store_dwordx4 v[36:37], v[26:29], off
	s_nop 1
	v_pk_fma_f32 v[26:27], v[68:69], v[38:39], v[76:77] op_sel_hi:[1, 0, 1]
	v_pk_fma_f32 v[28:29], v[66:67], v[38:39], v[74:75] op_sel_hi:[1, 0, 1]
	v_pk_fma_f32 v[24:25], v[24:25], v[240:241], v[26:27] op_sel:[0, 1, 0]
	v_pk_fma_f32 v[22:23], v[22:23], v[240:241], v[28:29] op_sel:[0, 1, 0]
	v_pk_fma_f32 v[26:27], v[52:53], v[38:39], v[60:61] op_sel_hi:[1, 0, 1]
	v_pk_fma_f32 v[28:29], v[50:51], v[38:39], v[58:59] op_sel_hi:[1, 0, 1]
	v_pk_fma_f32 v[26:27], v[20:21], v[240:241], v[26:27] op_sel:[0, 1, 0]
	v_pk_fma_f32 v[20:21], v[18:19], v[240:241], v[28:29] op_sel:[0, 1, 0]
	v_cvt_pk_bf16_f32 v18, v22, v23
	v_cvt_pk_bf16_f32 v19, v24, v25
	s_nop 0
	v_cvt_pk_bf16_f32 v20, v20, v21
	v_cvt_pk_bf16_f32 v21, v26, v27
	global_store_dwordx4 v[36:37], v[18:21], off offset:256
	s_nop 1
	v_add_u32_e32 v18, 0xb0, v166
	v_ashrrev_i32_e32 v19, 31, v18
	v_mad_i64_i32 v[20:21], s[0:1], v18, s2, v[162:163]
	v_lshl_add_u64 v[20:21], v[20:21], 0, v[164:165]
	s_mov_b64 s[2:3], -1
	v_mul_f32_e64 v22, v197, -v196
	v_pk_fma_f32 v[24:25], v[72:73], v[22:23], v[80:81] op_sel_hi:[1, 0, 1]
	v_pk_fma_f32 v[26:27], v[70:71], v[22:23], v[78:79] op_sel_hi:[1, 0, 1]
	v_pk_fma_f32 v[16:17], v[16:17], v[196:197], v[24:25] op_sel:[0, 1, 0]
	v_pk_fma_f32 v[14:15], v[14:15], v[196:197], v[26:27] op_sel:[0, 1, 0]
	v_pk_fma_f32 v[24:25], v[56:57], v[22:23], v[64:65] op_sel_hi:[1, 0, 1]
	v_pk_fma_f32 v[26:27], v[54:55], v[22:23], v[62:63] op_sel_hi:[1, 0, 1]
	v_pk_fma_f32 v[24:25], v[12:13], v[196:197], v[24:25] op_sel:[0, 1, 0]
	v_pk_fma_f32 v[12:13], v[10:11], v[196:197], v[26:27] op_sel:[0, 1, 0]
	v_cvt_pk_bf16_f32 v10, v14, v15
	v_cvt_pk_bf16_f32 v11, v16, v17
	s_nop 0
	v_cvt_pk_bf16_f32 v12, v12, v13
	v_cvt_pk_bf16_f32 v13, v24, v25
	global_store_dwordx4 v[20:21], v[10:13], off
	s_nop 1
	v_pk_fma_f32 v[10:11], v[68:69], v[22:23], v[76:77] op_sel_hi:[1, 0, 1]
	v_pk_fma_f32 v[12:13], v[66:67], v[22:23], v[74:75] op_sel_hi:[1, 0, 1]
	v_pk_fma_f32 v[8:9], v[8:9], v[196:197], v[10:11] op_sel:[0, 1, 0]
	v_pk_fma_f32 v[6:7], v[6:7], v[196:197], v[12:13] op_sel:[0, 1, 0]
	v_pk_fma_f32 v[10:11], v[52:53], v[22:23], v[60:61] op_sel_hi:[1, 0, 1]
	v_pk_fma_f32 v[12:13], v[50:51], v[22:23], v[58:59] op_sel_hi:[1, 0, 1]
	v_pk_fma_f32 v[10:11], v[4:5], v[196:197], v[10:11] op_sel:[0, 1, 0]
	v_pk_fma_f32 v[4:5], v[2:3], v[196:197], v[12:13] op_sel:[0, 1, 0]
	v_cvt_pk_bf16_f32 v2, v6, v7
	v_cvt_pk_bf16_f32 v3, v8, v9
	s_nop 0
	v_cvt_pk_bf16_f32 v4, v4, v5
	v_cvt_pk_bf16_f32 v5, v10, v11
	global_store_dwordx4 v[20:21], v[2:5], off offset:256
	s_cbranch_vccnz .LBB0_248
	s_andn2_b64 vcc, exec, s[4:5]
	s_cbranch_vccnz .LBB0_247
	s_barrier
	s_branch .LBB0_247

; #define LAS __attribute__((address_space(3)))
; __device__ __forceinline__ float sx(float v, int mask, int lane) { return __int_as_float(__builtin_amdgcn_ds_bpermute((lane ^ mask) << 2, __float_as_int(v))); }
; __device__ __forceinline__ void diff_task(const bf16_t* proj, bf16_t* xo, int b, int h, int qb, float lam, float post, const float* g_diff, int  , LAS unsigned char* vl) {
;     ...
;     float ss = 0.f;
; #pragma unroll
;     for (int db = 0; db < 4; ++db)
; #pragma unroll
;         for (int r = 0; r < 16; ++r) ss += ot[db][r] * ot[db][r];
;     ss += sx(ss, 32, lane);
; __global__ void __launch_bounds__(NWAVES * 64, 2) mega_fwd(Params P) {
;     ...
;             PH_IDS
;             const float a1 = wave_sum(P.in[4][l * 64 + lane] * P.in[5][l * 64 + lane], lane);
;             const float a2 = wave_sum(P.in[6][l * 64 + lane] * P.in[7][l * 64 + lane], lane);
;             const float lam = __int_as_float(__builtin_amdgcn_readfirstlane(__float_as_int(__expf(a1) - __expf(a2) + lam_init)));
;             const float* gdf = P.in[8] + l * 128;
;             LAS unsigned char* vl = lds + wave * WAVE_LDS;
;             const int vgw = (((bx & 7) * (G / 8)) + (bx >> 3)) * NWAVES + wave;
;             for (int task = vgw; task < NB * 8 * 32; task += NGW) {
.LBB0_311:
	s_or_b64 exec, exec, s[4:5]
	v_readlane_b32 s0, v254, 25
	s_waitcnt lgkmcnt(0)
	s_barrier
	v_mbcnt_lo_u32_b32 v0, -1, 0
	v_mbcnt_hi_u32_b32 v0, -1, v0
	v_readlane_b32 s36, v249, 2
	v_lshl_add_u32 v2, s0, 6, v0
	v_ashrrev_i32_e32 v3, 31, v2
	v_lshlrev_b64 v[2:3], 2, v[2:3]
	v_readlane_b32 s44, v249, 10
	v_readlane_b32 s45, v249, 11
	v_readlane_b32 s46, v249, 12
	v_readlane_b32 s47, v249, 13
	v_lshl_add_u64 v[4:5], s[44:45], 0, v[2:3]
	v_readlane_b32 s48, v249, 14
	v_readlane_b32 s49, v249, 15
	v_readlane_b32 s50, v249, 16
	v_readlane_b32 s51, v249, 17
	global_load_dword v6, v[4:5], off
	v_lshl_add_u64 v[4:5], s[46:47], 0, v[2:3]
	global_load_dword v7, v[4:5], off
	v_lshl_add_u64 v[4:5], s[48:49], 0, v[2:3]
	v_lshl_add_u64 v[2:3], s[50:51], 0, v[2:3]
	global_load_dword v4, v[4:5], off
	v_lshlrev_b32_e32 v0, 2, v0
	global_load_dword v2, v[2:3], off
	v_xor_b32_e32 v3, 4, v0
	s_lshl_b32 s2, s0, 7
	s_mov_b32 s3, s29
	v_writelane_b32 v255, s2, 24
	v_readlane_b32 s14, v250, 51
	v_readlane_b32 s15, v250, 54
	v_writelane_b32 v255, s3, 25
	v_readlane_b32 s16, v250, 55
	v_readlane_b32 s17, v250, 56
	v_readlane_b32 s18, v250, 57
	v_readlane_b32 s19, v253, 40
	v_readlane_b32 s21, v253, 39
	v_readlane_b32 s22, v253, 41
	s_mov_b32 s24, 0x18000
	s_mov_b32 s25, 0xc000
	s_movk_i32 s26, 0x110
	s_movk_i32 s27, 0x140
	s_mov_b32 s30, 0x24000
	s_mov_b32 s31, 0x3c000
	s_mov_b32 s33, 0x48000
	s_mov_b32 s34, 0x54000
	s_mov_b32 s35, 0x3fffffc
	s_sub_u32 s22, s22, 1
	s_or_b32 s22, s22, 7
	s_add_u32 s22, s22, 1
	v_readlane_b32 s37, v249, 3
	v_readlane_b32 s38, v249, 4
	v_readlane_b32 s39, v249, 5
	v_readlane_b32 s40, v249, 6
	v_readlane_b32 s41, v249, 7
	v_readlane_b32 s42, v249, 8
	v_readlane_b32 s43, v249, 9
	s_waitcnt vmcnt(2)
	v_mul_f32_e32 v5, v6, v7
	ds_bpermute_b32 v5, v3, v5
	s_waitcnt vmcnt(0)
	v_mul_f32_e32 v8, v4, v2
	ds_bpermute_b32 v3, v3, v8
	v_xor_b32_e32 v8, 8, v0
	s_waitcnt lgkmcnt(1)
	v_fmac_f32_e32 v5, v6, v7
	v_xor_b32_e32 v6, 16, v0
	v_xor_b32_e32 v7, 64, v0
	s_waitcnt lgkmcnt(0)
	v_fmac_f32_e32 v3, v4, v2
	ds_bpermute_b32 v2, v8, v5
	ds_bpermute_b32 v4, v8, v3
	s_waitcnt lgkmcnt(1)
	v_add_f32_e32 v2, v5, v2
	s_waitcnt lgkmcnt(0)
	v_add_f32_e32 v3, v3, v4
	ds_bpermute_b32 v4, v6, v2
	ds_bpermute_b32 v5, v6, v3
	v_xor_b32_e32 v6, 32, v0
	v_xor_b32_e32 v0, 0x80, v0
	s_waitcnt lgkmcnt(1)
	v_add_f32_e32 v2, v2, v4
	s_waitcnt lgkmcnt(0)
	v_add_f32_e32 v3, v3, v5
	ds_bpermute_b32 v4, v6, v2
	ds_bpermute_b32 v5, v6, v3
	v_cvt_f32_u32_e32 v6, s0
	v_readlane_b32 s0, v250, 52
	v_readlane_b32 s1, v250, 53
	s_waitcnt lgkmcnt(1)
	v_add_f32_e32 v2, v2, v4
	s_waitcnt lgkmcnt(0)
	v_add_f32_e32 v3, v3, v5
	ds_bpermute_b32 v4, v7, v2
	ds_bpermute_b32 v5, v7, v3
	s_andn2_b64 vcc, exec, s[0:1]
	s_waitcnt lgkmcnt(1)
	v_add_f32_e32 v2, v2, v4
	s_waitcnt lgkmcnt(0)
	v_add_f32_e32 v3, v3, v5
	ds_bpermute_b32 v4, v0, v2
	ds_bpermute_b32 v0, v0, v3
	v_mul_f32_e32 v5, 0xbe99999a, v6
	v_mul_f32_e32 v5, 0x3fb8aa3b, v5
	v_exp_f32_e32 v5, v5
	s_waitcnt lgkmcnt(1)
	v_add_f32_e32 v2, v2, v4
	s_waitcnt lgkmcnt(0)
	v_add_f32_e32 v0, v3, v0
	v_mul_f32_e32 v2, 0x3fb8aa3b, v2
	v_mul_f32_e32 v0, 0x3fb8aa3b, v0
	v_exp_f32_e32 v2, v2
	v_exp_f32_e32 v3, v0
	v_fmamk_f32 v0, v5, 0xbf19999a, v243
	v_sub_f32_e32 v2, v2, v3
	v_add_f32_e32 v2, v0, v2
	s_nop 0
	v_readfirstlane_b32 s6, v2
	s_cbranch_vccnz .LBB0_342
	v_readlane_b32 s0, v255, 24
	v_readlane_b32 s1, v255, 25
	s_lshl_b64 s[0:1], s[0:1], 2
	v_readlane_b32 s36, v249, 18
	v_readlane_b32 s37, v249, 19
	s_add_u32 s36, s36, s0
	s_addc_u32 s37, s37, s1
	v_sub_f32_e32 v178, 1.0, v0
	v_readlane_b32 s7, v250, 58
	v_readlane_b32 s38, v249, 20
	v_readlane_b32 s39, v249, 21
	v_readlane_b32 s40, v249, 22
	v_readlane_b32 s41, v249, 23
	v_readlane_b32 s42, v249, 24
	v_readlane_b32 s43, v249, 25
	v_readlane_b32 s44, v249, 26
	v_readlane_b32 s45, v249, 27
	v_readlane_b32 s46, v249, 28
	v_readlane_b32 s47, v249, 29
	v_readlane_b32 s48, v249, 30
	v_readlane_b32 s49, v249, 31
	v_readlane_b32 s50, v249, 32
	v_readlane_b32 s51, v249, 33
	s_branch .LBB0_314
.LBB0_313:
	v_mul_f32_e32 v0, v51, v51
	v_fmac_f32_e32 v0, v50, v50
	v_fmac_f32_e32 v0, v52, v52
	v_fmac_f32_e32 v0, v53, v53
	v_fmac_f32_e32 v0, v54, v54
	v_fmac_f32_e32 v0, v55, v55
	v_fmac_f32_e32 v0, v56, v56
	v_fmac_f32_e32 v0, v57, v57
	v_fmac_f32_e32 v0, v58, v58
	v_fmac_f32_e32 v0, v59, v59
	v_fmac_f32_e32 v0, v60, v60
	v_fmac_f32_e32 v0, v61, v61
	v_fmac_f32_e32 v0, v62, v62
	v_fmac_f32_e32 v0, v63, v63
	v_fmac_f32_e32 v0, v64, v64
	v_fmac_f32_e32 v0, v65, v65
	v_fmac_f32_e32 v0, v34, v34
	v_fmac_f32_e32 v0, v35, v35
	v_fmac_f32_e32 v0, v36, v36
	v_fmac_f32_e32 v0, v37, v37
	v_fmac_f32_e32 v0, v38, v38
	v_fmac_f32_e32 v0, v39, v39
	v_fmac_f32_e32 v0, v40, v40
	v_fmac_f32_e32 v0, v41, v41
	v_fmac_f32_e32 v0, v42, v42
	v_fmac_f32_e32 v0, v43, v43
	v_fmac_f32_e32 v0, v44, v44
	v_fmac_f32_e32 v0, v45, v45
	v_fmac_f32_e32 v0, v46, v46
	v_fmac_f32_e32 v0, v47, v47
	v_fmac_f32_e32 v0, v48, v48
	v_fmac_f32_e32 v0, v49, v49
	v_fmac_f32_e32 v0, v18, v18
	v_fmac_f32_e32 v0, v19, v19
	v_fmac_f32_e32 v0, v20, v20
	v_fmac_f32_e32 v0, v21, v21
	v_fmac_f32_e32 v0, v22, v22
	v_fmac_f32_e32 v0, v23, v23
	v_fmac_f32_e32 v0, v24, v24
	v_fmac_f32_e32 v0, v25, v25
	v_fmac_f32_e32 v0, v26, v26
	v_fmac_f32_e32 v0, v27, v27
	v_fmac_f32_e32 v0, v28, v28
	v_fmac_f32_e32 v0, v29, v29
	v_fmac_f32_e32 v0, v30, v30
	v_fmac_f32_e32 v0, v31, v31
	v_fmac_f32_e32 v0, v32, v32
	v_fmac_f32_e32 v0, v33, v33
	v_fmac_f32_e32 v0, v2, v2
	v_fmac_f32_e32 v0, v3, v3
	v_fmac_f32_e32 v0, v4, v4
	v_fmac_f32_e32 v0, v5, v5
	v_fmac_f32_e32 v0, v6, v6
	v_fmac_f32_e32 v0, v7, v7
	v_fmac_f32_e32 v0, v8, v8
	v_fmac_f32_e32 v0, v9, v9
	v_fmac_f32_e32 v0, v10, v10
	v_fmac_f32_e32 v0, v11, v11
	v_fmac_f32_e32 v0, v12, v12
	v_fmac_f32_e32 v0, v13, v13
	v_fmac_f32_e32 v0, v14, v14
	v_fmac_f32_e32 v0, v15, v15
	v_fmac_f32_e32 v0, v16, v16
	v_fmac_f32_e32 v0, v17, v17
	ds_bpermute_b32 v66, v212, v0
	v_ashrrev_i32_e32 v167, 31, v166
	s_mov_b32 s73, s29
	s_waitcnt lgkmcnt(0)
; __device__ __forceinline__ float sx(float v, int mask, int lane) { return __int_as_float(__builtin_amdgcn_ds_bpermute((lane ^ mask) << 2, __float_as_int(v))); }
; __device__ __forceinline__ unsigned cvt_pk_bf16(float lo, float hi) { unsigned r; asm volatile("v_cvt_pk_bf16_f32 %0, %1, %2" : "=v"(r) : "v"(lo), "v"(hi)); return r; }
; __device__ __forceinline__ void diff_task(const bf16_t* proj, bf16_t* xo, int b, int h, int qb, float lam, float post, const float* g_diff, int  , LAS unsigned char* vl) {
;     ...
;     float ss = 0.f;
; #pragma unroll
;     for (int db = 0; db < 4; ++db)
; #pragma unroll
;         for (int r = 0; r < 16; ++r) ss += ot[db][r] * ot[db][r];
;     ss += sx(ss, 32, lane);
;     const float rn = (1.0f / sqrtf(ss * (1.f / 128.f) + RMS_EPS)) * post;
;     bf16_t* op = xo + (rowb + qpos) * DM + h * 128;
;     u32x2 o2[16];
; #pragma unroll
;     for (int db = 0; db < 4; ++db)
; #pragma unroll
;         for (int rg = 0; rg < 4; ++rg) { const int d = 32 * db + 8 * rg + 4 * hi; const f32x4 gg = *(const f32x4*)(g_diff + d);
;             u32x2 w; w.x = pg8::cvt_pk_bf16(ot[db][4 * rg] * rn * gg[0], ot[db][4 * rg + 1] * rn * gg[1]); w.y = pg8::cvt_pk_bf16(ot[db][4 * rg + 2] * rn * gg[2], ot[db][4 * rg + 3] * rn * gg[3]);
;             o2[4 * db + rg] = w; }
;     store_rows_wide(op, o2, hi);
	v_add_f32_e32 v0, v0, v66
	v_fmamk_f32 v0, v0, 0x3c000000, v244
	v_cmp_gt_f32_e32 vcc, s12, v0
	v_mul_f32_e32 v66, 0x4f800000, v0
	s_nop 0
	v_cndmask_b32_e32 v0, v0, v66, vcc
	v_sqrt_f32_e32 v66, v0
	s_nop 0
	v_add_u32_e32 v67, -1, v66
	v_fma_f32 v68, -v67, v66, v0
	v_cmp_ge_f32_e64 s[4:5], 0, v68
	v_add_u32_e32 v68, 1, v66
	s_nop 0
	v_cndmask_b32_e64 v67, v66, v67, s[4:5]
	v_fma_f32 v66, -v68, v66, v0
	v_cmp_lt_f32_e64 s[4:5], 0, v66
	s_nop 1
	v_cndmask_b32_e64 v66, v67, v68, s[4:5]
	v_mul_f32_e32 v67, 0x37800000, v66
	v_cndmask_b32_e32 v66, v66, v67, vcc
	v_cmp_class_f32_e32 vcc, v0, v245
	s_nop 1
	v_cndmask_b32_e32 v0, v66, v0, vcc
	v_div_scale_f32 v66, s[0:1], v0, v0, 1.0
	v_rcp_f32_e32 v67, v66
	s_add_i32 s0, s7, 0x800
	s_cmpk_gt_i32 s7, 0x7ff
	s_mov_b32 s7, s0
	v_fma_f32 v68, -v66, v67, 1.0
	v_fmac_f32_e32 v67, v68, v67
	v_div_scale_f32 v68, vcc, 1.0, v0, 1.0
	v_mul_f32_e32 v69, v68, v67
	v_fma_f32 v70, -v66, v69, v68
	v_fmac_f32_e32 v69, v70, v67
	v_fma_f32 v66, -v66, v69, v68
	v_div_fmas_f32 v66, v66, v67, v69
	v_lshl_add_u64 v[70:71], v[166:167], 2, s[36:37]
	v_div_fixup_f32 v0, v66, v0, 1.0
	global_load_dwordx4 v[74:77], v[70:71], off
	global_load_dwordx4 v[78:81], v[70:71], off offset:32
	global_load_dwordx4 v[82:85], v[70:71], off offset:64
	global_load_dwordx4 v[86:89], v[70:71], off offset:96
	global_load_dwordx4 v[90:93], v[70:71], off offset:128
	global_load_dwordx4 v[94:97], v[70:71], off offset:160
	global_load_dwordx4 v[146:149], v[70:71], off offset:192
	global_load_dwordx4 v[150:153], v[70:71], off offset:224
	global_load_dwordx4 v[154:157], v[70:71], off offset:256
	global_load_dwordx4 v[158:161], v[70:71], off offset:288
	global_load_dwordx4 v[234:237], v[70:71], off offset:320
	global_load_dwordx4 v[238:241], v[70:71], off offset:352
	global_load_dwordx4 v[98:101], v[70:71], off offset:384
	global_load_dwordx4 v[102:105], v[70:71], off offset:416
	global_load_dwordx4 v[106:109], v[70:71], off offset:448
	global_load_dwordx4 v[110:113], v[70:71], off offset:480
	v_mul_f32_e32 v0, v178, v0
	v_mul_f32_e32 v50, v50, v0
	v_mul_f32_e32 v51, v51, v0
	v_mul_f32_e32 v58, v58, v0
	v_mul_f32_e32 v34, v34, v0
	v_mul_f32_e32 v35, v35, v0
	v_mul_f32_e32 v42, v42, v0
	v_mul_f32_e32 v18, v18, v0
	v_mul_f32_e32 v19, v19, v0
	v_mul_f32_e32 v26, v26, v0
	v_mul_f32_e32 v2, v2, v0
	v_mul_f32_e32 v3, v3, v0
	v_mul_f32_e32 v10, v10, v0
	s_waitcnt vmcnt(15)
	v_mul_f32_e32 v50, v74, v50
	v_mul_f32_e32 v51, v75, v51
	v_cvt_pk_bf16_f32 v50, v50, v51
	v_mul_f32_e32 v51, v52, v0
	v_mul_f32_e32 v51, v76, v51
	v_mul_f32_e32 v52, v53, v0
	v_mul_f32_e32 v52, v77, v52
	v_cvt_pk_bf16_f32 v51, v51, v52
	v_mul_f32_e32 v52, v54, v0
	v_mul_f32_e32 v53, v55, v0
	v_mul_f32_e32 v54, v57, v0
	s_waitcnt vmcnt(14)
	v_mul_f32_e32 v52, v78, v52
	v_mul_f32_e32 v53, v79, v53
	v_cvt_pk_bf16_f32 v52, v52, v53
	v_mul_f32_e32 v53, v56, v0
	v_mul_f32_e32 v53, v80, v53
	v_mul_f32_e32 v54, v81, v54
	v_cvt_pk_bf16_f32 v53, v53, v54
	s_nop 1
	v_permlane32_swap_b32_e32 v50, v52
	v_permlane32_swap_b32_e32 v51, v53
	s_waitcnt vmcnt(13)
	v_mul_f32_e32 v54, v82, v58
	v_mul_f32_e32 v58, v59, v0
	v_mul_f32_e32 v55, v83, v58
	v_cvt_pk_bf16_f32 v54, v54, v55
	v_mul_f32_e32 v55, v60, v0
	v_mul_f32_e32 v55, v84, v55
	v_mul_f32_e32 v56, v61, v0
	v_mul_f32_e32 v56, v85, v56
	v_cvt_pk_bf16_f32 v55, v55, v56
	v_mul_f32_e32 v60, v62, v0
	s_waitcnt vmcnt(12)
	v_mul_f32_e32 v56, v60, v86
	v_mul_f32_e32 v60, v63, v0
	v_mul_f32_e32 v57, v60, v87
	v_cvt_pk_bf16_f32 v56, v56, v57
	v_mul_f32_e32 v57, v64, v0
	v_mul_f32_e32 v57, v57, v88
	v_mul_f32_e32 v58, v65, v0
	v_mul_f32_e32 v58, v58, v89
	v_cvt_pk_bf16_f32 v57, v57, v58
	s_nop 1
	v_permlane32_swap_b32_e32 v54, v56
	v_permlane32_swap_b32_e32 v55, v57
	s_waitcnt vmcnt(11)
	v_mul_f32_e32 v34, v34, v90
	v_mul_f32_e32 v35, v35, v91
	v_cvt_pk_bf16_f32 v34, v34, v35
	v_mul_f32_e32 v35, v36, v0
	v_mul_f32_e32 v35, v35, v92
	v_mul_f32_e32 v36, v37, v0
	v_mul_f32_e32 v36, v36, v93
	v_cvt_pk_bf16_f32 v35, v35, v36
	v_mul_f32_e32 v36, v38, v0
	v_mul_f32_e32 v37, v39, v0
	v_mul_f32_e32 v38, v41, v0
	s_waitcnt vmcnt(10)
; __device__ __forceinline__ unsigned cvt_pk_bf16(float lo, float hi) { unsigned r; asm volatile("v_cvt_pk_bf16_f32 %0, %1, %2" : "=v"(r) : "v"(lo), "v"(hi)); return r; }
; __device__ __forceinline__ void store_rows_wide(bf16_t* op  , u32x2 (&o2)[16], int hi) {
; #pragma unroll
;     for (int k = 0; k < 16; k += 2) { u32x2 a = o2[k], b = o2[k + 1];
;         { auto r = __builtin_amdgcn_permlane32_swap(a.x, b.x, false, false); a.x = r[0]; b.x = r[1]; }
;         { auto r = __builtin_amdgcn_permlane32_swap(a.y, b.y, false, false); a.y = r[0]; b.y = r[1]; }
;         u32x4 w; w.x = a.x; w.y = a.y; w.z = b.x; w.w = b.y;
;         *(u32x4*)(op + 8 * k + 8 * hi) = w; }
; }
; __device__ __forceinline__ void diff_task(const bf16_t* proj, bf16_t* xo, int b, int h, int qb, float lam, float post, const float* g_diff, int  , LAS unsigned char* vl) {
;     ...
;     bf16_t* op = xo + (rowb + qpos) * DM + h * 128;
;     u32x2 o2[16];
; #pragma unroll
;     for (int db = 0; db < 4; ++db)
; #pragma unroll
;         for (int rg = 0; rg < 4; ++rg) { const int d = 32 * db + 8 * rg + 4 * hi; const f32x4 gg = *(const f32x4*)(g_diff + d);
;             u32x2 w; w.x = pg8::cvt_pk_bf16(ot[db][4 * rg] * rn * gg[0], ot[db][4 * rg + 1] * rn * gg[1]); w.y = pg8::cvt_pk_bf16(ot[db][4 * rg + 2] * rn * gg[2], ot[db][4 * rg + 3] * rn * gg[3]);
;             o2[4 * db + rg] = w; }
;     store_rows_wide(op, o2, hi);
	v_mul_f32_e32 v36, v36, v94
	v_mul_f32_e32 v37, v37, v95
	v_cvt_pk_bf16_f32 v36, v36, v37
	v_mul_f32_e32 v37, v40, v0
	v_mul_f32_e32 v37, v37, v96
	v_mul_f32_e32 v38, v38, v97
	v_cvt_pk_bf16_f32 v37, v37, v38
	s_nop 1
	v_permlane32_swap_b32_e32 v34, v36
	v_permlane32_swap_b32_e32 v35, v37
	s_waitcnt vmcnt(9)
	v_mul_f32_e32 v38, v42, v146
	v_mul_f32_e32 v42, v43, v0
	v_mul_f32_e32 v39, v42, v147
	v_cvt_pk_bf16_f32 v38, v38, v39
	v_mul_f32_e32 v39, v44, v0
	v_mul_f32_e32 v39, v39, v148
	v_mul_f32_e32 v40, v45, v0
	v_mul_f32_e32 v40, v40, v149
	v_cvt_pk_bf16_f32 v39, v39, v40
	v_mul_f32_e32 v44, v46, v0
	s_waitcnt vmcnt(8)
	v_mul_f32_e32 v40, v44, v150
	v_mul_f32_e32 v44, v47, v0
	v_mul_f32_e32 v41, v44, v151
	v_cvt_pk_bf16_f32 v40, v40, v41
	v_mul_f32_e32 v41, v48, v0
	v_mul_f32_e32 v41, v41, v152
	v_mul_f32_e32 v42, v49, v0
	v_mul_f32_e32 v42, v42, v153
	v_cvt_pk_bf16_f32 v41, v41, v42
	s_nop 1
	v_permlane32_swap_b32_e32 v38, v40
	v_permlane32_swap_b32_e32 v39, v41
	s_waitcnt vmcnt(7)
	v_mul_f32_e32 v18, v18, v154
	v_mul_f32_e32 v19, v19, v155
	v_cvt_pk_bf16_f32 v18, v18, v19
	v_mul_f32_e32 v19, v20, v0
	v_mul_f32_e32 v19, v19, v156
	v_mul_f32_e32 v20, v21, v0
	v_mul_f32_e32 v20, v20, v157
	v_cvt_pk_bf16_f32 v19, v19, v20
	v_mul_f32_e32 v20, v22, v0
	v_mul_f32_e32 v21, v23, v0
	v_mul_f32_e32 v22, v25, v0
	s_waitcnt vmcnt(6)
	v_mul_f32_e32 v20, v20, v158
	v_mul_f32_e32 v21, v21, v159
	v_cvt_pk_bf16_f32 v20, v20, v21
	v_mul_f32_e32 v21, v24, v0
	v_mul_f32_e32 v21, v21, v160
	v_mul_f32_e32 v22, v22, v161
	v_cvt_pk_bf16_f32 v21, v21, v22
	s_nop 1
	v_permlane32_swap_b32_e32 v18, v20
	v_permlane32_swap_b32_e32 v19, v21
	s_waitcnt vmcnt(5)
	v_mul_f32_e32 v22, v26, v234
	v_mul_f32_e32 v26, v27, v0
	v_mul_f32_e32 v23, v26, v235
	v_cvt_pk_bf16_f32 v22, v22, v23
	v_mul_f32_e32 v23, v28, v0
	v_mul_f32_e32 v23, v23, v236
	v_mul_f32_e32 v24, v29, v0
	v_mul_f32_e32 v24, v24, v237
	v_cvt_pk_bf16_f32 v23, v23, v24
	v_mul_f32_e32 v28, v30, v0
	s_waitcnt vmcnt(4)
	v_mul_f32_e32 v24, v28, v238
	v_mul_f32_e32 v28, v31, v0
	v_mul_f32_e32 v25, v28, v239
	v_cvt_pk_bf16_f32 v24, v24, v25
	v_mul_f32_e32 v25, v32, v0
	v_mul_f32_e32 v25, v25, v240
	v_mul_f32_e32 v26, v33, v0
	v_mul_f32_e32 v26, v26, v241
	v_cvt_pk_bf16_f32 v25, v25, v26
	s_nop 1
	v_permlane32_swap_b32_e32 v22, v24
	v_permlane32_swap_b32_e32 v23, v25
	s_waitcnt vmcnt(3)
	v_mul_f32_e32 v2, v2, v98
	v_mul_f32_e32 v3, v3, v99
	v_cvt_pk_bf16_f32 v2, v2, v3
	v_mul_f32_e32 v3, v4, v0
	v_mul_f32_e32 v3, v3, v100
	v_mul_f32_e32 v4, v5, v0
	v_mul_f32_e32 v4, v4, v101
	v_cvt_pk_bf16_f32 v3, v3, v4
	v_mul_f32_e32 v4, v6, v0
	v_mul_f32_e32 v5, v7, v0
	v_mul_f32_e32 v6, v9, v0
	s_waitcnt vmcnt(2)
	v_mul_f32_e32 v4, v4, v102
	v_mul_f32_e32 v5, v5, v103
	v_cvt_pk_bf16_f32 v4, v4, v5
	v_mul_f32_e32 v5, v8, v0
	v_mul_f32_e32 v5, v5, v104
	v_mul_f32_e32 v6, v6, v105
	v_cvt_pk_bf16_f32 v5, v5, v6
	s_nop 1
	v_permlane32_swap_b32_e32 v2, v4
	v_permlane32_swap_b32_e32 v3, v5
	s_waitcnt vmcnt(1)
	v_mul_f32_e32 v6, v10, v106
	v_mul_f32_e32 v10, v11, v0
	v_mul_f32_e32 v7, v10, v107
	v_cvt_pk_bf16_f32 v6, v6, v7
	v_mul_f32_e32 v7, v12, v0
	v_mul_f32_e32 v7, v7, v108
	v_mul_f32_e32 v8, v13, v0
	v_mul_f32_e32 v8, v8, v109
	v_cvt_pk_bf16_f32 v7, v7, v8
	v_mul_f32_e32 v12, v14, v0
	s_waitcnt vmcnt(0)
	v_mul_f32_e32 v8, v12, v110
	v_mul_f32_e32 v12, v15, v0
	v_mul_f32_e32 v9, v12, v111
	v_cvt_pk_bf16_f32 v8, v8, v9
	v_mul_f32_e32 v9, v16, v0
	v_mul_f32_e32 v0, v17, v0
	v_mul_f32_e32 v9, v9, v112
	v_mul_f32_e32 v0, v0, v113
	v_lshlrev_b64 v[10:11], 12, v[162:163]
	v_lshl_add_u64 v[10:11], s[8:9], 0, v[10:11]
	v_cvt_pk_bf16_f32 v9, v9, v0
	v_lshl_add_u64 v[10:11], v[10:11], 0, s[72:73]
	v_lshl_add_u64 v[10:11], v[164:165], 1, v[10:11]
	s_nop 1
	v_permlane32_swap_b32_e32 v6, v8
	v_permlane32_swap_b32_e32 v7, v9
	global_store_dwordx4 v[10:11], v[50:53], off
	global_store_dwordx4 v[10:11], v[54:57], off offset:32
	global_store_dwordx4 v[10:11], v[34:37], off offset:64
	global_store_dwordx4 v[10:11], v[38:41], off offset:96
	global_store_dwordx4 v[10:11], v[18:21], off offset:128
	global_store_dwordx4 v[10:11], v[22:25], off offset:160
	global_store_dwordx4 v[10:11], v[2:5], off offset:192
	global_store_dwordx4 v[10:11], v[6:9], off offset:224
	s_cbranch_scc1 .LBB0_342

; #define LAS __attribute__((address_space(3)))
; __device__ __forceinline__ float sx(float v, int mask, int lane) { return __int_as_float(__builtin_amdgcn_ds_bpermute((lane ^ mask) << 2, __float_as_int(v))); }
; __device__ __forceinline__ void diff_task(const bf16_t* proj, bf16_t* xo, int b, int h, int qb, float lam, float post, const float* g_diff, int  , LAS unsigned char* vl) {
;     ...
;     { const float mo0 = sx(m0, 32, lane), lo0 = sx(l0, 32, lane), mo1 = sx(m1, 32, lane), lo1 = sx(l1, 32, lane);
;       const float M0 = fmaxf(m0, mo0), M1 = fmaxf(m1, mo1);
;       l0 = l0 * __builtin_amdgcn_exp2f(m0 - M0) + lo0 * __builtin_amdgcn_exp2f(mo0 - M0); l1 = l1 * __builtin_amdgcn_exp2f(m1 - M1) + lo1 * __builtin_amdgcn_exp2f(mo1 - M1); m0 = M0; m1 = M1; }
;     const float i0 = 1.0f / l0, i1 = lam / l1;
;     f32x16 ot[4];
; #pragma unroll
;     for (int db = 0; db < 4; ++db) ot[db] = (f32x16){};
;     const int g = lane >> 4, ii = lane & 15;
;     const LAS unsigned char* vtb = vl + (4 * (g >> 1) + (ii >> 2)) * VROWB + (16 * (g & 1) + 4 * (ii & 3)) * 2;
;     u32x4 vr[8];
;     load_v(vr, vcol, 1, voff);
;     load_v(kr, kcol, 1, voff);
;     store_v(vl, vr, lane);
;     store_k(kl, kr, lane);
;     sh = 0.f;
.LBB0_324:
	s_lshl_b32 s72, s0, 1
	s_add_u32 s0, s17, s72
	s_addc_u32 s1, s18, 0
	s_add_u32 s74, s0, s4
	s_addc_u32 s75, s1, s5
	v_lshl_add_u64 v[222:223], s[74:75], 0, v[0:1]
	v_add_co_u32_e32 v6, vcc, s25, v222
	v_lshlrev_b32_e32 v72, 2, v152
	s_nop 0
	v_addc_co_u32_e32 v7, vcc, 0, v223, vcc
	v_add_co_u32_e32 v10, vcc, s24, v222
	global_load_dwordx4 v[2:5], v[222:223], off
	s_nop 0
	global_load_dwordx4 v[6:9], v[6:7], off
	v_addc_co_u32_e32 v11, vcc, 0, v223, vcc
	v_add_co_u32_e32 v14, vcc, s30, v222
	v_xor_b32_e32 v0, 0x80, v72
	s_nop 0
	v_addc_co_u32_e32 v15, vcc, 0, v223, vcc
	v_add_co_u32_e32 v18, vcc, s10, v222
	global_load_dwordx4 v[10:13], v[10:11], off
	s_nop 0
	global_load_dwordx4 v[14:17], v[14:15], off
	v_addc_co_u32_e32 v19, vcc, 0, v223, vcc
	v_add_co_u32_e32 v22, vcc, s31, v222
	ds_bpermute_b32 v69, v0, v155
	s_nop 0
	v_addc_co_u32_e32 v23, vcc, 0, v223, vcc
	v_add_co_u32_e32 v26, vcc, s33, v222
	global_load_dwordx4 v[18:21], v[18:19], off
	s_nop 0
	global_load_dwordx4 v[22:25], v[22:23], off
	v_addc_co_u32_e32 v27, vcc, 0, v223, vcc
	v_add_co_u32_e32 v30, vcc, s34, v222
	ds_bpermute_b32 v71, v0, v156
	s_nop 0
	v_addc_co_u32_e32 v31, vcc, 0, v223, vcc
	global_load_dwordx4 v[26:29], v[26:27], off
	s_nop 0
	global_load_dwordx4 v[30:33], v[30:31], off
	s_nop 0
	global_load_dwordx4 v[34:37], v[204:205], off
	global_load_dwordx4 v[38:41], v[130:131], off
	global_load_dwordx4 v[42:45], v[132:133], off
	global_load_dwordx4 v[46:49], v[134:135], off
	global_load_dwordx4 v[50:53], v[136:137], off
	global_load_dwordx4 v[54:57], v[138:139], off
	global_load_dwordx4 v[58:61], v[140:141], off
	global_load_dwordx4 v[62:65], v[142:143], off
	s_waitcnt lgkmcnt(1)
	v_max_f32_e32 v68, v69, v69
	v_max_f32_e32 v70, v155, v155
	v_max_f32_e32 v229, v70, v68
	s_waitcnt lgkmcnt(0)
	v_max_f32_e32 v68, v71, v71
	v_max_f32_e32 v70, v156, v156
	v_max_f32_e32 v230, v70, v68
	ds_bpermute_b32 v66, v0, v144
	ds_bpermute_b32 v67, v0, v145
	v_sub_f32_e32 v69, v69, v229
	v_sub_f32_e32 v71, v71, v230
	v_sub_f32_e32 v68, v155, v229
	v_exp_f32_e32 v70, v69
	v_sub_f32_e32 v69, v156, v230
	v_exp_f32_e32 v71, v71
	v_exp_f32_e32 v68, v68
	v_exp_f32_e32 v69, v69
	v_mov_b32_e32 v231, 0
	s_waitcnt lgkmcnt(0)
	v_pk_mul_f32 v[66:67], v[70:71], v[66:67]
	s_waitcnt vmcnt(15)
	ds_write_b128 v227, v[2:5]
	s_waitcnt vmcnt(14)
	ds_write_b128 v227, v[6:9] offset:1280
	s_waitcnt vmcnt(13)
	ds_write_b128 v227, v[10:13] offset:2560
	s_waitcnt vmcnt(12)
	ds_write_b128 v227, v[14:17] offset:3840
	s_waitcnt vmcnt(11)
	ds_write_b128 v227, v[18:21] offset:5120
	s_waitcnt vmcnt(10)
	ds_write_b128 v227, v[22:25] offset:6400
	s_waitcnt vmcnt(9)
	ds_write_b128 v227, v[26:29] offset:7680
	s_waitcnt vmcnt(8)
	ds_write_b128 v227, v[30:33] offset:8960
	s_waitcnt vmcnt(7)
	ds_write_b128 v167, v[34:37] offset:10240
	s_waitcnt vmcnt(6)
	ds_write_b128 v167, v[38:41] offset:11328
	s_waitcnt vmcnt(5)
	ds_write_b128 v167, v[42:45] offset:12416
	s_waitcnt vmcnt(4)
	ds_write_b128 v167, v[46:49] offset:13504
	s_waitcnt vmcnt(3)
	ds_write_b128 v167, v[50:53] offset:14592
	s_waitcnt vmcnt(2)
	ds_write_b128 v167, v[54:57] offset:15680
	s_waitcnt vmcnt(1)
	ds_write_b128 v167, v[58:61] offset:16768
	s_waitcnt vmcnt(0)
	ds_write_b128 v167, v[62:65] offset:17856
	v_pk_fma_f32 v[66:67], v[146:147], v[68:69], v[66:67]
	v_mov_b32_e32 v2, 0
	v_div_scale_f32 v68, s[0:1], v67, v67, s6
	v_rcp_f32_e32 v69, v68
	v_mov_b32_e32 v3, 0
	v_mov_b32_e32 v4, 0
	v_mov_b32_e32 v5, 0
	v_fma_f32 v70, -v68, v69, 1.0
	v_fmac_f32_e32 v69, v70, v69
	v_div_scale_f32 v70, vcc, s6, v67, s6
	v_mul_f32_e32 v71, v70, v69
	v_fma_f32 v73, -v68, v71, v70
	v_fmac_f32_e32 v71, v73, v69
	v_fma_f32 v68, -v68, v71, v70
	v_div_scale_f32 v70, s[0:1], v66, v66, 1.0
	v_rcp_f32_e32 v73, v70
	v_div_fmas_f32 v68, v68, v69, v71
	v_div_fixup_f32 v225, v68, v67, s6
	s_mov_b32 s0, 0
	v_fma_f32 v67, -v70, v73, 1.0
	v_fmac_f32_e32 v73, v67, v73
	v_div_scale_f32 v67, vcc, 1.0, v66, 1.0
	v_mul_f32_e32 v68, v67, v73
	v_fma_f32 v69, -v70, v68, v67
	v_fmac_f32_e32 v68, v69, v73
	v_fma_f32 v67, -v70, v68, v67
	v_div_fmas_f32 v67, v67, v73, v68
	v_div_fixup_f32 v224, v67, v66, 1.0
	v_lshrrev_b32_e32 v66, 3, v152
	v_lshrrev_b32_e32 v67, 2, v153
	v_and_or_b32 v66, v66, s35, v67
	v_and_b32_e32 v67, 16, v152
	v_mul_lo_u32 v66, v66, s27
	v_and_or_b32 v67, v72, 12, v67
	v_add_u32_e32 v66, s14, v66
	v_lshlrev_b32_e32 v67, 1, v67
	v_mov_b32_e32 v6, 0
	v_mov_b32_e32 v7, 0
	v_mov_b32_e32 v8, 0
	v_mov_b32_e32 v9, 0
	v_mov_b32_e32 v10, 0
	v_mov_b32_e32 v11, 0
	v_mov_b32_e32 v12, 0
	v_mov_b32_e32 v13, 0
	v_mov_b32_e32 v14, 0
	v_mov_b32_e32 v15, 0
	v_mov_b32_e32 v16, 0
	v_mov_b32_e32 v17, 0
	v_mov_b32_e32 v18, 0
	v_mov_b32_e32 v19, 0
	v_mov_b32_e32 v20, 0
	v_mov_b32_e32 v21, 0
	v_mov_b32_e32 v22, 0
	v_mov_b32_e32 v23, 0
	v_mov_b32_e32 v24, 0
	v_mov_b32_e32 v25, 0
	v_mov_b32_e32 v26, 0
	v_mov_b32_e32 v27, 0
	v_mov_b32_e32 v28, 0
	v_mov_b32_e32 v29, 0
	v_mov_b32_e32 v30, 0
	v_mov_b32_e32 v31, 0
	v_mov_b32_e32 v32, 0
	v_mov_b32_e32 v33, 0
	v_mov_b32_e32 v34, 0
	v_mov_b32_e32 v35, 0
	v_mov_b32_e32 v36, 0
	v_mov_b32_e32 v37, 0
	v_mov_b32_e32 v38, 0
	v_mov_b32_e32 v39, 0
	v_mov_b32_e32 v40, 0
	v_mov_b32_e32 v41, 0
	v_mov_b32_e32 v42, 0
	v_mov_b32_e32 v43, 0
	v_mov_b32_e32 v44, 0
	v_mov_b32_e32 v45, 0
	v_mov_b32_e32 v46, 0
	v_mov_b32_e32 v47, 0
	v_mov_b32_e32 v48, 0
	v_mov_b32_e32 v49, 0
	v_mov_b32_e32 v50, 0
	v_mov_b32_e32 v51, 0
	v_mov_b32_e32 v52, 0
	v_mov_b32_e32 v53, 0
	v_mov_b32_e32 v54, 0
	v_mov_b32_e32 v55, 0
	v_mov_b32_e32 v56, 0
	v_mov_b32_e32 v57, 0
	v_mov_b32_e32 v58, 0
	v_mov_b32_e32 v59, 0
	v_mov_b32_e32 v60, 0
	v_mov_b32_e32 v61, 0
	v_mov_b32_e32 v62, 0
	v_mov_b32_e32 v63, 0
	v_mov_b32_e32 v64, 0
	v_mov_b32_e32 v65, 0
	v_add_u32_e32 v232, v66, v67
	s_and_b32 s80, s7, 7
	s_mul_i32 s81, s80, 0xc000
	s_mul_i32 s82, s80, 0x45c0
	s_mul_i32 s83, s80, 0x4500
	v_subrev_u32_e32 v154, s82, v167
	v_add_u32_e32 v155, 0xde00, v154
	v_add_u32_e32 v156, 0x1bc00, v154
	v_subrev_u32_e32 v157, s83, v227
	v_add_u32_e32 v160, 0x12800, v157
	s_branch .LBB0_326
; #define LAS __attribute__((address_space(3)))
; #define MFMA32(a, b, c) __builtin_amdgcn_mfma_f32_32x32x16_bf16((a), (b), (c), 0, 0, 0)
; __device__ __forceinline__ s16x4 vtr(const LAS unsigned char* p) { return __builtin_bit_cast(s16x4, __builtin_amdgcn_ds_read_tr16_b64_v4i16((LAS s16x4*)p)); }
; __device__ __forceinline__ void pv_chunk(f32x16 (&ot)[4], const LAS unsigned char* vtb, bf16x8 pf0, bf16x8 pf1) {
; #pragma unroll
;     for (int db = 0; db < 4; ++db)
; #pragma unroll
;         for (int s = 0; s < 2; ++s) {
;             const s16x4 a = vtr(vtb + (16 * s) * VROWB + 64 * db), b2 = vtr(vtb + (16 * s + 8) * VROWB + 64 * db);
;             const bf16x8 vf = (bf16x8){a[0], a[1], a[2], a[3], b2[0], b2[1], b2[2], b2[3]};
;             __builtin_amdgcn_s_setprio(1); ot[db] = MFMA32(vf, s ? pf1 : pf0, ot[db]); __builtin_amdgcn_s_setprio(0);
;         }
; }
; __device__ __forceinline__ void diff_task(const bf16_t* proj, bf16_t* xo, int b, int h, int qb, float lam, float post, const float* g_diff, int  , LAS unsigned char* vl) {
;     ...
;         const float e0 = m0 - sh, e1 = m1 - sh;
;         float p[16];
; #pragma unroll
;         for (int r = 0; r < 16; ++r) { const float bq0 = B0(r) - e0, bq1 = B0(r) - e1; p[r] = __builtin_amdgcn_exp2f(s0[r] * c1 + bq0) * i0 - __builtin_amdgcn_exp2f(s1[r] * c1 + bq1) * i1; }
;         bf16x8 pf0 = pack8(p), pf1 = pack8(p + 8);
;         asm volatile("" : "+v"(pf0), "+v"(pf1));
;         load_v(vr, vcol + (size_t)(kn * 32) * NIN, 1, voff);
;         pv_chunk(ot, vtb, pf0, pf1);
;         store_k(kl, kr, lane);
;         store_v(vl, vr, lane);
;         sh += c2s;
.LBB0_325:
	ds_read_b64_tr_b16 v[134:135], v232
	ds_read_b64_tr_b16 v[136:137], v232 offset:2560
	ds_read_b64_tr_b16 v[138:139], v232 offset:5120
	ds_read_b64_tr_b16 v[140:141], v232 offset:7680
	ds_read_b64_tr_b16 v[142:143], v232 offset:64
	ds_read_b64_tr_b16 v[144:145], v232 offset:2624
	ds_read_b64_tr_b16 v[146:147], v232 offset:5184
	ds_read_b64_tr_b16 v[148:149], v232 offset:7744
	ds_read_b64_tr_b16 v[150:151], v232 offset:128
	ds_read_b64_tr_b16 v[152:153], v232 offset:2688
	v_sub_f32_e32 v186, v229, v231
	v_sub_f32_e32 v187, v230, v231
	v_sub_f32_e32 v184, v206, v186
	v_sub_f32_e32 v185, v206, v187
	v_fmac_f32_e32 v184, 0x3e38aa3b, v82
	v_fmac_f32_e32 v185, 0x3e38aa3b, v66
	v_exp_f32_e32 v184, v184
	v_exp_f32_e32 v185, v185
	v_sub_f32_e32 v82, v207, v187
	v_sub_f32_e32 v66, v207, v186
	v_fmac_f32_e32 v82, 0x3e38aa3b, v67
	v_fmac_f32_e32 v66, 0x3e38aa3b, v83
	v_exp_f32_e32 v67, v82
	v_pk_mul_f32 v[82:83], v[224:225], v[184:185]
	v_exp_f32_e32 v66, v66
	v_sub_f32_e32 v184, v82, v83
	v_sub_f32_e32 v82, v208, v186
	v_sub_f32_e32 v83, v208, v187
	v_fmac_f32_e32 v82, 0x3e38aa3b, v84
	v_fmac_f32_e32 v83, 0x3e38aa3b, v68
	v_sub_f32_e32 v68, v209, v186
	v_sub_f32_e32 v84, v209, v187
	v_exp_f32_e32 v82, v82
	v_exp_f32_e32 v83, v83
	v_fmac_f32_e32 v68, 0x3e38aa3b, v85
	v_fmac_f32_e32 v84, 0x3e38aa3b, v69
	v_exp_f32_e32 v68, v68
	v_exp_f32_e32 v69, v84
	v_pk_mul_f32 v[66:67], v[224:225], v[66:67]
	s_nop 0
	v_sub_f32_e32 v84, v66, v67
	v_pk_mul_f32 v[66:67], v[224:225], v[82:83]
	v_sub_f32_e32 v83, v211, v187
	v_sub_f32_e32 v82, v66, v67
	v_pk_mul_f32 v[66:67], v[224:225], v[68:69]
	v_sub_f32_e32 v68, v210, v186
	v_sub_f32_e32 v69, v210, v187
	v_fmac_f32_e32 v68, 0x3e38aa3b, v86
	v_fmac_f32_e32 v69, 0x3e38aa3b, v70
	v_sub_f32_e32 v70, v211, v186
	v_exp_f32_e32 v68, v68
	v_exp_f32_e32 v69, v69
	v_fmac_f32_e32 v70, 0x3e38aa3b, v87
	v_fmac_f32_e32 v83, 0x3e38aa3b, v71
	v_exp_f32_e32 v70, v70
	v_exp_f32_e32 v71, v83
	v_sub_f32_e32 v83, v66, v67
	v_pk_mul_f32 v[66:67], v[224:225], v[68:69]
	v_sub_f32_e32 v68, v212, v186
	v_sub_f32_e32 v69, v212, v187
	v_sub_f32_e32 v85, v66, v67
	v_pk_mul_f32 v[66:67], v[224:225], v[70:71]
	v_fmac_f32_e32 v68, 0x3e38aa3b, v88
	v_fmac_f32_e32 v69, 0x3e38aa3b, v72
	v_sub_f32_e32 v70, v213, v186
	v_sub_f32_e32 v71, v213, v187
	v_exp_f32_e32 v68, v68
	v_exp_f32_e32 v69, v69
	v_fmac_f32_e32 v70, 0x3e38aa3b, v89
	v_fmac_f32_e32 v71, 0x3e38aa3b, v73
	v_exp_f32_e32 v70, v70
	v_exp_f32_e32 v71, v71
	v_sub_f32_e32 v72, v66, v67
	v_pk_mul_f32 v[66:67], v[224:225], v[68:69]
	v_sub_f32_e32 v68, v214, v186
	v_sub_f32_e32 v69, v214, v187
	v_sub_f32_e32 v73, v66, v67
	v_pk_mul_f32 v[66:67], v[224:225], v[70:71]
	v_fmac_f32_e32 v68, 0x3e38aa3b, v90
	v_fmac_f32_e32 v69, 0x3e38aa3b, v74
	v_sub_f32_e32 v70, v215, v186
	v_sub_f32_e32 v71, v215, v187
	v_exp_f32_e32 v68, v68
	v_exp_f32_e32 v69, v69
	v_fmac_f32_e32 v70, 0x3e38aa3b, v91
	v_fmac_f32_e32 v71, 0x3e38aa3b, v75
	v_exp_f32_e32 v70, v70
	v_exp_f32_e32 v71, v71
	v_sub_f32_e32 v74, v66, v67
	v_pk_mul_f32 v[66:67], v[224:225], v[68:69]
	v_sub_f32_e32 v68, v216, v186
	v_sub_f32_e32 v69, v216, v187
	v_sub_f32_e32 v75, v66, v67
	v_pk_mul_f32 v[66:67], v[224:225], v[70:71]
	v_fmac_f32_e32 v68, 0x3e38aa3b, v92
	v_fmac_f32_e32 v69, 0x3e38aa3b, v76
	v_sub_f32_e32 v70, v217, v186
	v_sub_f32_e32 v71, v217, v187
	v_exp_f32_e32 v68, v68
	v_exp_f32_e32 v69, v69
	v_fmac_f32_e32 v70, 0x3e38aa3b, v93
	v_fmac_f32_e32 v71, 0x3e38aa3b, v77
	v_exp_f32_e32 v70, v70
	v_exp_f32_e32 v71, v71
	v_sub_f32_e32 v76, v66, v67
	v_pk_mul_f32 v[66:67], v[224:225], v[68:69]
	v_sub_f32_e32 v68, v218, v186
	v_sub_f32_e32 v69, v218, v187
	v_sub_f32_e32 v77, v66, v67
	v_pk_mul_f32 v[66:67], v[224:225], v[70:71]
	v_fmac_f32_e32 v68, 0x3e38aa3b, v94
	v_fmac_f32_e32 v69, 0x3e38aa3b, v78
	v_sub_f32_e32 v70, v219, v186
	v_sub_f32_e32 v71, v219, v187
	v_exp_f32_e32 v68, v68
	v_exp_f32_e32 v69, v69
	v_fmac_f32_e32 v70, 0x3e38aa3b, v95
	v_fmac_f32_e32 v71, 0x3e38aa3b, v79
	v_exp_f32_e32 v70, v70
	v_exp_f32_e32 v71, v71
	v_sub_f32_e32 v78, v66, v67
	v_pk_mul_f32 v[66:67], v[224:225], v[68:69]
	v_sub_f32_e32 v68, v220, v186
	v_sub_f32_e32 v69, v220, v187
	v_sub_f32_e32 v79, v66, v67
	v_pk_mul_f32 v[66:67], v[224:225], v[70:71]
	v_fmac_f32_e32 v68, 0x3e38aa3b, v96
	v_fmac_f32_e32 v69, 0x3e38aa3b, v80
	v_sub_f32_e32 v70, v221, v186
	v_sub_f32_e32 v71, v221, v187
	v_exp_f32_e32 v68, v68
	v_exp_f32_e32 v69, v69
	v_fmac_f32_e32 v70, 0x3e38aa3b, v97
	v_fmac_f32_e32 v71, 0x3e38aa3b, v81
	v_exp_f32_e32 v70, v70
	v_exp_f32_e32 v71, v71
	v_sub_f32_e32 v80, v66, v67
	v_pk_mul_f32 v[66:67], v[224:225], v[68:69]
	s_nop 0
	v_sub_f32_e32 v81, v66, v67
	v_pk_mul_f32 v[66:67], v[224:225], v[70:71]
	s_nop 0
	v_sub_f32_e32 v86, v66, v67
	v_cvt_pk_bf16_f32 v66, v184, v84
	v_lshl_add_u64 v[184:185], s[2:3], 1, v[222:223]
	v_cvt_pk_bf16_f32 v67, v82, v83
	v_cvt_pk_bf16_f32 v68, v85, v72
	v_cvt_pk_bf16_f32 v69, v73, v74
	v_cvt_pk_bf16_f32 v70, v75, v76
	v_cvt_pk_bf16_f32 v71, v77, v78
	v_cvt_pk_bf16_f32 v72, v79, v80
	v_cvt_pk_bf16_f32 v73, v81, v86
	v_add_co_u32_e32 v184, vcc, s81, v184
	s_nop 1
	v_addc_co_u32_e32 v185, vcc, 0, v185, vcc
	global_load_dwordx4 v[74:77], v[184:185], off
	ds_read_b64_tr_b16 v[78:79], v232 offset:5248
	ds_read_b64_tr_b16 v[80:81], v232 offset:7808
	ds_read_b64_tr_b16 v[82:83], v232 offset:192
	ds_read_b64_tr_b16 v[84:85], v232 offset:2752
	ds_read_b64_tr_b16 v[86:87], v232 offset:5312
	ds_read_b64_tr_b16 v[88:89], v232 offset:7872
	s_setprio 1
	s_waitcnt lgkmcnt(6)
	v_mfma_f32_32x32x16_bf16 v[50:65], v[134:137], v[66:69], v[50:65]
	v_mfma_f32_32x32x16_bf16 v[50:65], v[138:141], v[70:73], v[50:65]
	v_mfma_f32_32x32x16_bf16 v[34:49], v[142:145], v[66:69], v[34:49]
	v_mfma_f32_32x32x16_bf16 v[34:49], v[146:149], v[70:73], v[34:49]
	v_mfma_f32_32x32x16_bf16 v[18:33], v[150:153], v[66:69], v[18:33]
	s_waitcnt lgkmcnt(4)
	v_mfma_f32_32x32x16_bf16 v[18:33], v[78:81], v[70:73], v[18:33]
	s_waitcnt lgkmcnt(2)
	v_mfma_f32_32x32x16_bf16 v[2:17], v[82:85], v[66:69], v[2:17]
	s_waitcnt lgkmcnt(0)
	v_mfma_f32_32x32x16_bf16 v[2:17], v[86:89], v[70:73], v[2:17]
	s_setprio 0
	s_cmp_lg_u32 s22, s0
	v_add_f32_e32 v231, v226, v231
	s_barrier
	s_waitcnt vmcnt(1)
	ds_write_b128 v154, v[130:133] offset:10240
	ds_write_b128 v154, v[130:133] offset:29184
	ds_write_b128 v154, v[130:133] offset:48128
	ds_write_b128 v155, v[130:133] offset:10240
	ds_write_b128 v155, v[130:133] offset:29184
	ds_write_b128 v155, v[130:133] offset:48128
	ds_write_b128 v156, v[130:133] offset:10240
	ds_write_b128 v156, v[130:133] offset:29184
	s_waitcnt vmcnt(0)
	ds_write_b128 v157, v[74:77]
	ds_write_b128 v157, v[74:77] offset:18944
	ds_write_b128 v157, v[74:77] offset:37888
	ds_write_b128 v157, v[74:77] offset:56832
	ds_write_b128 v160, v[74:77]
	ds_write_b128 v160, v[74:77] offset:18944
	ds_write_b128 v160, v[74:77] offset:37888
	ds_write_b128 v160, v[74:77] offset:56832
	s_waitcnt lgkmcnt(0)
	s_barrier
	s_cbranch_scc0 .LBB0_328
; #define MFMA32(a, b, c) __builtin_amdgcn_mfma_f32_32x32x16_bf16((a), (b), (c), 0, 0, 0)
; __device__ __forceinline__ int crow(int r, int hi) { return (r & 3) + 8 * (r >> 2) + 4 * hi; }
; __device__ __forceinline__ void diff_task(const bf16_t* proj, bf16_t* xo, int b, int h, int qb, float lam, float post, const float* g_diff, int  , LAS unsigned char* vl) {
;     ...
;     for (int kc = 0; kc <= qb; ++kc) {
;         read_kf(kf, klane);
;         f32x16 s0 = {}, s1 = {};
; #pragma unroll
;         for (int d0 = 0; d0 < 4; ++d0) { s0 = MFMA32(kf[d0], qf[d0], s0); s1 = MFMA32(kf[4 + d0], qf[4 + d0], s1); }
;         const int kn = kc < qb ? kc + 1 : kc;
;         load_v(kr, kcol + (size_t)(kn * 32) * NIN, 1, voff);
;         if (kc == qb) {
; #pragma unroll
;             for (int r = 0; r < 16; ++r) if (crow(r, hi) > r32) { s0[r] = NEGBIG; s1[r] = NEGBIG; }
;         }
.LBB0_326:
	ds_read_b128 v[66:69], v228 offset:10240
	ds_read_b128 v[130:133], v228 offset:10272
	ds_read_b128 v[134:137], v228 offset:10304
	ds_read_b128 v[138:141], v228 offset:10336
	ds_read_b128 v[70:73], v228 offset:10368
	ds_read_b128 v[142:145], v228 offset:10400
	ds_read_b128 v[146:149], v228 offset:10432
	ds_read_b128 v[150:153], v228 offset:10464
	s_waitcnt lgkmcnt(7)
	v_mfma_f32_32x32x16_bf16 v[82:97], v[66:69], v[98:101], 0
	s_mov_b32 s1, s0
	s_add_i32 s0, s0, 1
	s_cmp_lt_u32 s0, s22
	s_cselect_b32 s2, s0, s1
	s_lshl_b32 s3, s2, 5
	s_mul_i32 s2, s2, 0x30000
	s_mul_hi_u32 s3, s3, 0x1800
	s_waitcnt lgkmcnt(3)
	v_mfma_f32_32x32x16_bf16 v[66:81], v[70:73], v[114:117], 0
	v_lshl_add_u64 v[158:159], s[2:3], 1, v[204:205]
	s_cmp_lg_u32 s19, s1
	v_mfma_f32_32x32x16_bf16 v[82:97], v[130:133], v[102:105], v[82:97]
	v_add_co_u32_e32 v158, vcc, s81, v158
	s_waitcnt lgkmcnt(2)
	v_mfma_f32_32x32x16_bf16 v[66:81], v[142:145], v[118:121], v[66:81]
	v_mfma_f32_32x32x16_bf16 v[82:97], v[134:137], v[106:109], v[82:97]
	v_addc_co_u32_e32 v159, vcc, 0, v159, vcc
	global_load_dwordx4 v[130:133], v[158:159], off
	s_waitcnt lgkmcnt(1)
	v_mfma_f32_32x32x16_bf16 v[66:81], v[146:149], v[122:125], v[66:81]
	v_mfma_f32_32x32x16_bf16 v[82:97], v[138:141], v[110:113], v[82:97]
	s_waitcnt lgkmcnt(0)
	v_mfma_f32_32x32x16_bf16 v[66:81], v[150:153], v[126:129], v[66:81]
	s_nop 7
	s_nop 3
	s_cbranch_scc1 .Lpb1_chk
	v_cndmask_b32_e64 v184, v82, v248, s[38:39]
	v_cndmask_b32_e64 v185, v66, v248, s[38:39]
	v_cndmask_b32_e64 v83, v248, v83, s[42:43]
	v_cndmask_b32_e64 v82, v184, v82, s[42:43]
	v_cndmask_b32_e64 v67, v248, v67, s[42:43]
	v_cndmask_b32_e64 v66, v185, v66, s[42:43]
	v_cndmask_b32_e64 v84, v84, v248, s[44:45]
	v_cndmask_b32_e64 v68, v68, v248, s[44:45]
	v_cndmask_b32_e64 v85, v85, v248, s[46:47]
	v_cndmask_b32_e64 v69, v69, v248, s[46:47]
	v_cndmask_b32_e64 v86, v86, v248, s[48:49]
	v_cndmask_b32_e64 v70, v70, v248, s[48:49]
	v_cndmask_b32_e64 v87, v87, v248, s[50:51]
	v_cndmask_b32_e64 v71, v71, v248, s[50:51]
	v_cndmask_b32_e64 v88, v88, v248, s[52:53]
	v_cndmask_b32_e64 v72, v72, v248, s[52:53]
	v_cndmask_b32_e64 v89, v89, v248, s[54:55]
	v_cndmask_b32_e64 v73, v73, v248, s[54:55]
	v_cndmask_b32_e64 v90, v90, v248, s[56:57]
	v_cndmask_b32_e64 v74, v74, v248, s[56:57]
	v_cndmask_b32_e64 v91, v91, v248, s[58:59]
	v_cndmask_b32_e64 v75, v75, v248, s[58:59]
	v_cndmask_b32_e64 v92, v92, v248, s[60:61]
	v_cndmask_b32_e64 v76, v76, v248, s[60:61]
	v_cndmask_b32_e64 v93, v93, v248, s[62:63]
	v_cndmask_b32_e64 v77, v77, v248, s[62:63]
	v_cndmask_b32_e64 v94, v94, v248, s[64:65]
	v_cndmask_b32_e64 v78, v78, v248, s[64:65]
	v_cndmask_b32_e64 v95, v95, v248, s[66:67]
	v_cndmask_b32_e64 v79, v79, v248, s[66:67]
	v_cndmask_b32_e64 v96, v96, v248, s[68:69]
	v_cndmask_b32_e64 v80, v80, v248, s[68:69]
	v_cndmask_b32_e64 v97, v97, v248, s[70:71]
	v_cndmask_b32_e64 v81, v81, v248, s[70:71]
	s_branch .LBB0_325
.Lpb1_chk:
	s_cmp_gt_u32 s1, s19
	s_cbranch_scc0 .LBB0_325
	v_mov_b32_e32 v66, v248
	v_mov_b32_e32 v67, v248
	v_mov_b32_e32 v68, v248
	v_mov_b32_e32 v69, v248
	v_mov_b32_e32 v70, v248
	v_mov_b32_e32 v71, v248
	v_mov_b32_e32 v72, v248
	v_mov_b32_e32 v73, v248
	v_mov_b32_e32 v74, v248
	v_mov_b32_e32 v75, v248
	v_mov_b32_e32 v76, v248
	v_mov_b32_e32 v77, v248
	v_mov_b32_e32 v78, v248
	v_mov_b32_e32 v79, v248
	v_mov_b32_e32 v80, v248
	v_mov_b32_e32 v81, v248
	v_mov_b32_e32 v82, v248
	v_mov_b32_e32 v83, v248
	v_mov_b32_e32 v84, v248
	v_mov_b32_e32 v85, v248
	v_mov_b32_e32 v86, v248
	v_mov_b32_e32 v87, v248
	v_mov_b32_e32 v88, v248
	v_mov_b32_e32 v89, v248
	v_mov_b32_e32 v90, v248
	v_mov_b32_e32 v91, v248
	v_mov_b32_e32 v92, v248
	v_mov_b32_e32 v93, v248
	v_mov_b32_e32 v94, v248
	v_mov_b32_e32 v95, v248
	v_mov_b32_e32 v96, v248
	v_mov_b32_e32 v97, v248
	s_branch .LBB0_325
.LBB0_328:
	v_mul_f32_e32 v66, v51, v51
	v_fmac_f32_e32 v66, v50, v50
	v_fmac_f32_e32 v66, v52, v52
	v_fmac_f32_e32 v66, v53, v53
	v_fmac_f32_e32 v66, v54, v54
	v_fmac_f32_e32 v66, v55, v55
	v_fmac_f32_e32 v66, v56, v56
	v_fmac_f32_e32 v66, v57, v57
	v_fmac_f32_e32 v66, v58, v58
	v_fmac_f32_e32 v66, v59, v59
	v_fmac_f32_e32 v66, v60, v60
	v_fmac_f32_e32 v66, v61, v61
	v_fmac_f32_e32 v66, v62, v62
	v_fmac_f32_e32 v66, v63, v63
	v_fmac_f32_e32 v66, v64, v64
	v_fmac_f32_e32 v66, v65, v65
	v_fmac_f32_e32 v66, v34, v34
	v_fmac_f32_e32 v66, v35, v35
	v_fmac_f32_e32 v66, v36, v36
	v_fmac_f32_e32 v66, v37, v37
	v_fmac_f32_e32 v66, v38, v38
	v_fmac_f32_e32 v66, v39, v39
	v_fmac_f32_e32 v66, v40, v40
	v_fmac_f32_e32 v66, v41, v41
	v_fmac_f32_e32 v66, v42, v42
	v_fmac_f32_e32 v66, v43, v43
	v_fmac_f32_e32 v66, v44, v44
	v_fmac_f32_e32 v66, v45, v45
	v_fmac_f32_e32 v66, v46, v46
	v_fmac_f32_e32 v66, v47, v47
	v_fmac_f32_e32 v66, v48, v48
	v_fmac_f32_e32 v66, v49, v49
	v_fmac_f32_e32 v66, v18, v18
	v_fmac_f32_e32 v66, v19, v19
	v_fmac_f32_e32 v66, v20, v20
	v_fmac_f32_e32 v66, v21, v21
	v_fmac_f32_e32 v66, v22, v22
	v_fmac_f32_e32 v66, v23, v23
	v_fmac_f32_e32 v66, v24, v24
	v_fmac_f32_e32 v66, v25, v25
	v_fmac_f32_e32 v66, v26, v26
	v_fmac_f32_e32 v66, v27, v27
	v_fmac_f32_e32 v66, v28, v28
	v_fmac_f32_e32 v66, v29, v29
	v_fmac_f32_e32 v66, v30, v30
	v_fmac_f32_e32 v66, v31, v31
	v_fmac_f32_e32 v66, v32, v32
	v_fmac_f32_e32 v66, v33, v33
	v_fmac_f32_e32 v66, v2, v2
	v_fmac_f32_e32 v66, v3, v3
	v_fmac_f32_e32 v66, v4, v4
	v_fmac_f32_e32 v66, v5, v5
	v_fmac_f32_e32 v66, v6, v6
	v_fmac_f32_e32 v66, v7, v7
	v_fmac_f32_e32 v66, v8, v8
	v_fmac_f32_e32 v66, v9, v9
	v_fmac_f32_e32 v66, v10, v10
	v_fmac_f32_e32 v66, v11, v11
	v_fmac_f32_e32 v66, v12, v12
	v_fmac_f32_e32 v66, v13, v13
	v_fmac_f32_e32 v66, v14, v14
	v_fmac_f32_e32 v66, v15, v15
	v_fmac_f32_e32 v66, v16, v16
	v_fmac_f32_e32 v66, v17, v17
	ds_bpermute_b32 v0, v0, v66
	v_ashrrev_i32_e32 v167, 31, v166
	v_readlane_b32 s2, v249, 34
	v_readlane_b32 s3, v249, 35
	s_mov_b32 s73, s29
	s_waitcnt lgkmcnt(0)
; __device__ __forceinline__ float sx(float v, int mask, int lane) { return __int_as_float(__builtin_amdgcn_ds_bpermute((lane ^ mask) << 2, __float_as_int(v))); }
; __device__ __forceinline__ unsigned cvt_pk_bf16(float lo, float hi) { unsigned r; asm volatile("v_cvt_pk_bf16_f32 %0, %1, %2" : "=v"(r) : "v"(lo), "v"(hi)); return r; }
; __device__ __forceinline__ void diff_task(const bf16_t* proj, bf16_t* xo, int b, int h, int qb, float lam, float post, const float* g_diff, int  , LAS unsigned char* vl) {
;     ...
;     float ss = 0.f;
; #pragma unroll
;     for (int db = 0; db < 4; ++db)
; #pragma unroll
;         for (int r = 0; r < 16; ++r) ss += ot[db][r] * ot[db][r];
;     ss += sx(ss, 32, lane);
;     const float rn = (1.0f / sqrtf(ss * (1.f / 128.f) + RMS_EPS)) * post;
;     bf16_t* op = xo + (rowb + qpos) * DM + h * 128;
;     u32x2 o2[16];
; #pragma unroll
;     for (int db = 0; db < 4; ++db)
; #pragma unroll
;         for (int rg = 0; rg < 4; ++rg) { const int d = 32 * db + 8 * rg + 4 * hi; const f32x4 gg = *(const f32x4*)(g_diff + d);
;             u32x2 w; w.x = pg8::cvt_pk_bf16(ot[db][4 * rg] * rn * gg[0], ot[db][4 * rg + 1] * rn * gg[1]); w.y = pg8::cvt_pk_bf16(ot[db][4 * rg + 2] * rn * gg[2], ot[db][4 * rg + 3] * rn * gg[3]);
;             o2[4 * db + rg] = w; }
;     store_rows_wide(op, o2, hi);
	v_add_f32_e32 v0, v66, v0
	v_fmamk_f32 v0, v0, 0x3c000000, v244
	v_cmp_gt_f32_e32 vcc, s9, v0
	v_mul_f32_e32 v66, 0x4f800000, v0
	v_mov_b32_e32 v130, 0
	v_cndmask_b32_e32 v0, v0, v66, vcc
	v_sqrt_f32_e32 v66, v0
	s_mov_b32 s12, 0xf800000
	v_mov_b32_e32 v155, 0xf149f2ca
	v_mov_b32_e32 v156, 0xf149f2ca
	v_add_u32_e32 v67, -1, v66
	v_fma_f32 v68, -v67, v66, v0
	v_cmp_ge_f32_e64 s[4:5], 0, v68
	v_add_u32_e32 v68, 1, v66
	v_mov_b32_e32 v131, v130
	v_cndmask_b32_e64 v67, v66, v67, s[4:5]
	v_fma_f32 v66, -v68, v66, v0
	v_cmp_lt_f32_e64 s[4:5], 0, v66
	s_nop 1
	v_cndmask_b32_e64 v66, v67, v68, s[4:5]
	v_mul_f32_e32 v67, 0x37800000, v66
	v_cndmask_b32_e32 v66, v66, v67, vcc
	v_cmp_class_f32_e32 vcc, v0, v245
	s_xor_b32 s4, s8, 63
	s_movk_i32 s5, 0x3000
	v_cndmask_b32_e32 v0, v66, v0, vcc
	v_div_scale_f32 v66, s[0:1], v0, v0, 1.0
	v_rcp_f32_e32 v67, v66
	v_readlane_b32 s0, v254, 28
	v_readlane_b32 s1, v254, 29
	s_mov_b64 s[8:9], s[2:3]
	v_fma_f32 v68, -v66, v67, 1.0
	v_fmac_f32_e32 v67, v68, v67
	v_div_scale_f32 v68, vcc, 1.0, v0, 1.0
	v_mul_f32_e32 v69, v68, v67
	v_fma_f32 v70, -v66, v69, v68
	v_fmac_f32_e32 v69, v70, v67
	v_fma_f32 v66, -v66, v69, v68
	v_div_fmas_f32 v66, v66, v67, v69
	v_lshl_add_u64 v[70:71], v[166:167], 2, s[36:37]
	v_div_fixup_f32 v0, v66, v0, 1.0
	global_load_dwordx4 v[74:77], v[70:71], off
	global_load_dwordx4 v[78:81], v[70:71], off offset:32
	global_load_dwordx4 v[82:85], v[70:71], off offset:64
	global_load_dwordx4 v[86:89], v[70:71], off offset:96
	global_load_dwordx4 v[90:93], v[70:71], off offset:128
	global_load_dwordx4 v[94:97], v[70:71], off offset:160
	global_load_dwordx4 v[134:137], v[70:71], off offset:192
	global_load_dwordx4 v[138:141], v[70:71], off offset:224
	global_load_dwordx4 v[142:145], v[70:71], off offset:256
	global_load_dwordx4 v[146:149], v[70:71], off offset:288
	global_load_dwordx4 v[150:153], v[70:71], off offset:320
	global_load_dwordx4 v[158:161], v[70:71], off offset:352
	global_load_dwordx4 v[234:237], v[70:71], off offset:384
	global_load_dwordx4 v[238:241], v[70:71], off offset:416
	global_load_dwordx4 v[98:101], v[70:71], off offset:448
	global_load_dwordx4 v[102:105], v[70:71], off offset:480
	v_mul_f32_e32 v0, v178, v0
	v_mul_f32_e32 v50, v50, v0
	v_mul_f32_e32 v51, v51, v0
	v_mul_f32_e32 v58, v58, v0
	v_mul_f32_e32 v34, v34, v0
	v_mul_f32_e32 v35, v35, v0
	v_mul_f32_e32 v42, v42, v0
	v_mul_f32_e32 v18, v18, v0
	v_mul_f32_e32 v19, v19, v0
	v_mul_f32_e32 v26, v26, v0
	v_mul_f32_e32 v2, v2, v0
	v_mul_f32_e32 v3, v3, v0
	v_mul_f32_e32 v10, v10, v0
	s_waitcnt vmcnt(15)
	v_mul_f32_e32 v50, v74, v50
	v_mul_f32_e32 v51, v75, v51
	v_cvt_pk_bf16_f32 v50, v50, v51
	v_mul_f32_e32 v51, v52, v0
	v_mul_f32_e32 v51, v76, v51
	v_mul_f32_e32 v52, v53, v0
	v_mul_f32_e32 v52, v77, v52
	v_cvt_pk_bf16_f32 v51, v51, v52
	v_mul_f32_e32 v52, v54, v0
	v_mul_f32_e32 v53, v55, v0
	v_mul_f32_e32 v54, v57, v0
	s_waitcnt vmcnt(14)
	v_mul_f32_e32 v52, v78, v52
	v_mul_f32_e32 v53, v79, v53
	v_cvt_pk_bf16_f32 v52, v52, v53
	v_mul_f32_e32 v53, v56, v0
	v_mul_f32_e32 v53, v80, v53
	v_mul_f32_e32 v54, v81, v54
	v_cvt_pk_bf16_f32 v53, v53, v54
	s_nop 1
	v_permlane32_swap_b32_e32 v50, v52
	v_permlane32_swap_b32_e32 v51, v53
	s_waitcnt vmcnt(13)
	v_mul_f32_e32 v54, v82, v58
	v_mul_f32_e32 v58, v59, v0
	v_mul_f32_e32 v55, v83, v58
	v_cvt_pk_bf16_f32 v54, v54, v55
	v_mul_f32_e32 v55, v60, v0
	v_mul_f32_e32 v55, v84, v55
	v_mul_f32_e32 v56, v61, v0
	v_mul_f32_e32 v56, v85, v56
	v_cvt_pk_bf16_f32 v55, v55, v56
	v_mul_f32_e32 v60, v62, v0
	s_waitcnt vmcnt(12)
	v_mul_f32_e32 v56, v60, v86
	v_mul_f32_e32 v60, v63, v0
	v_mul_f32_e32 v57, v60, v87
	v_cvt_pk_bf16_f32 v56, v56, v57
	v_mul_f32_e32 v57, v64, v0
	v_mul_f32_e32 v57, v57, v88
	v_mul_f32_e32 v58, v65, v0
	v_mul_f32_e32 v58, v58, v89
	v_cvt_pk_bf16_f32 v57, v57, v58
	s_nop 1
	v_permlane32_swap_b32_e32 v54, v56
	v_permlane32_swap_b32_e32 v55, v57
	s_waitcnt vmcnt(11)
	v_mul_f32_e32 v34, v34, v90
	v_mul_f32_e32 v35, v35, v91
	v_cvt_pk_bf16_f32 v34, v34, v35
	v_mul_f32_e32 v35, v36, v0
	v_mul_f32_e32 v35, v35, v92
	v_mul_f32_e32 v36, v37, v0
	v_mul_f32_e32 v36, v36, v93
	v_cvt_pk_bf16_f32 v35, v35, v36
	v_mul_f32_e32 v36, v38, v0
	v_mul_f32_e32 v37, v39, v0
	v_mul_f32_e32 v38, v41, v0
	s_waitcnt vmcnt(10)
	v_mul_f32_e32 v36, v36, v94
	v_mul_f32_e32 v37, v37, v95
	v_cvt_pk_bf16_f32 v36, v36, v37
	v_mul_f32_e32 v37, v40, v0
	v_mul_f32_e32 v37, v37, v96
	v_mul_f32_e32 v38, v38, v97
	v_cvt_pk_bf16_f32 v37, v37, v38
	s_nop 1
	v_permlane32_swap_b32_e32 v34, v36
	v_permlane32_swap_b32_e32 v35, v37
	s_waitcnt vmcnt(9)
	v_mul_f32_e32 v38, v42, v134
	v_mul_f32_e32 v42, v43, v0
	v_mul_f32_e32 v39, v42, v135
	v_cvt_pk_bf16_f32 v38, v38, v39
	v_mul_f32_e32 v39, v44, v0
	v_mul_f32_e32 v39, v39, v136
	v_mul_f32_e32 v40, v45, v0
	v_mul_f32_e32 v40, v40, v137
	v_cvt_pk_bf16_f32 v39, v39, v40
	v_mul_f32_e32 v44, v46, v0
	s_waitcnt vmcnt(8)
	v_mul_f32_e32 v40, v44, v138
	v_mul_f32_e32 v44, v47, v0
	v_mul_f32_e32 v41, v44, v139
	v_cvt_pk_bf16_f32 v40, v40, v41
	v_mul_f32_e32 v41, v48, v0
	v_mul_f32_e32 v41, v41, v140
	v_mul_f32_e32 v42, v49, v0
	v_mul_f32_e32 v42, v42, v141
	v_cvt_pk_bf16_f32 v41, v41, v42
	s_nop 1
	v_permlane32_swap_b32_e32 v38, v40
	v_permlane32_swap_b32_e32 v39, v41
	s_waitcnt vmcnt(7)
	v_mul_f32_e32 v18, v18, v142
	v_mul_f32_e32 v19, v19, v143
	v_cvt_pk_bf16_f32 v18, v18, v19
	v_mul_f32_e32 v19, v20, v0
	v_mul_f32_e32 v19, v19, v144
	v_mul_f32_e32 v20, v21, v0
	v_mul_f32_e32 v20, v20, v145
	v_cvt_pk_bf16_f32 v19, v19, v20
	v_mul_f32_e32 v20, v22, v0
	v_mul_f32_e32 v21, v23, v0
	v_mul_f32_e32 v22, v25, v0
	s_waitcnt vmcnt(6)
; #define LAS __attribute__((address_space(3)))
; __device__ __forceinline__ unsigned cvt_pk_bf16(float lo, float hi) { unsigned r; asm volatile("v_cvt_pk_bf16_f32 %0, %1, %2" : "=v"(r) : "v"(lo), "v"(hi)); return r; }
; __device__ __forceinline__ void store_rows_wide(bf16_t* op  , u32x2 (&o2)[16], int hi) {
; #pragma unroll
;     for (int k = 0; k < 16; k += 2) { u32x2 a = o2[k], b = o2[k + 1];
;         { auto r = __builtin_amdgcn_permlane32_swap(a.x, b.x, false, false); a.x = r[0]; b.x = r[1]; }
;         { auto r = __builtin_amdgcn_permlane32_swap(a.y, b.y, false, false); a.y = r[0]; b.y = r[1]; }
;         u32x4 w; w.x = a.x; w.y = a.y; w.z = b.x; w.w = b.y;
;         *(u32x4*)(op + 8 * k + 8 * hi) = w; }
; }
; __device__ __forceinline__ void diff_task(const bf16_t* proj, bf16_t* xo, int b, int h, int qb, float lam, float post, const float* g_diff, int  , LAS unsigned char* vl) {
;     int lane; asm volatile("v_mbcnt_lo_u32_b32 %0, -1, 0\n\tv_mbcnt_hi_u32_b32 %0, -1, %0" : "=v"(lane));
;     const int r32 = lane & 31, hi = lane >> 5;
;     const size_t rowb = (size_t)b * SEQ;
;     const int qpos = qb * 32 + r32;
;     const float slope = exp2f(-(float)(2 * h + 1) * 0.5f);
;     const float c1 = 0.125f * LOG2E, c2 = slope * LOG2E, c2s = c2 * 32.f;
;     bf16x8 qf[8];
;     { const bf16_t* qp = proj + (rowb + qpos) * NIN + h * 128 + 8 * hi;
; #pragma unroll
;       for (int d0 = 0; d0 < 8; ++d0) qf[d0] = *(const bf16x8*)(qp + 16 * d0); }
;     const bf16_t* kcol = proj + 1024 + h * 128 + rowb * NIN;
;     const bf16_t* vcol = proj + 2048 + h * 128 + rowb * NIN;
;     const unsigned voff = (unsigned)((lane >> 4) * NIN + (lane & 15) * 8) * 2u;
;     ...
;     bf16_t* op = xo + (rowb + qpos) * DM + h * 128;
;     u32x2 o2[16];
; #pragma unroll
;     for (int db = 0; db < 4; ++db)
; #pragma unroll
;         for (int rg = 0; rg < 4; ++rg) { const int d = 32 * db + 8 * rg + 4 * hi; const f32x4 gg = *(const f32x4*)(g_diff + d);
;             u32x2 w; w.x = pg8::cvt_pk_bf16(ot[db][4 * rg] * rn * gg[0], ot[db][4 * rg + 1] * rn * gg[1]); w.y = pg8::cvt_pk_bf16(ot[db][4 * rg + 2] * rn * gg[2], ot[db][4 * rg + 3] * rn * gg[3]);
;             o2[4 * db + rg] = w; }
;     store_rows_wide(op, o2, hi);
	v_mul_f32_e32 v20, v20, v146
	v_mul_f32_e32 v21, v21, v147
	v_cvt_pk_bf16_f32 v20, v20, v21
	v_mul_f32_e32 v21, v24, v0
	v_mul_f32_e32 v21, v21, v148
	v_mul_f32_e32 v22, v22, v149
	v_cvt_pk_bf16_f32 v21, v21, v22
	s_nop 1
	v_permlane32_swap_b32_e32 v18, v20
	v_permlane32_swap_b32_e32 v19, v21
	s_waitcnt vmcnt(5)
	v_mul_f32_e32 v22, v26, v150
	v_mul_f32_e32 v26, v27, v0
	v_mul_f32_e32 v23, v26, v151
	v_cvt_pk_bf16_f32 v22, v22, v23
	v_mul_f32_e32 v23, v28, v0
	v_mul_f32_e32 v23, v23, v152
	v_mul_f32_e32 v24, v29, v0
	v_mul_f32_e32 v24, v24, v153
	v_cvt_pk_bf16_f32 v23, v23, v24
	v_mul_f32_e32 v28, v30, v0
	s_waitcnt vmcnt(4)
	v_mul_f32_e32 v24, v28, v158
	v_mul_f32_e32 v28, v31, v0
	v_mul_f32_e32 v25, v28, v159
	v_cvt_pk_bf16_f32 v24, v24, v25
	v_mul_f32_e32 v25, v32, v0
	v_mul_f32_e32 v25, v25, v160
	v_mul_f32_e32 v26, v33, v0
	v_mul_f32_e32 v26, v26, v161
	v_cvt_pk_bf16_f32 v25, v25, v26
	s_nop 1
	v_permlane32_swap_b32_e32 v22, v24
	v_permlane32_swap_b32_e32 v23, v25
	s_waitcnt vmcnt(3)
	v_mul_f32_e32 v2, v2, v234
	v_mul_f32_e32 v3, v3, v235
	v_cvt_pk_bf16_f32 v2, v2, v3
	v_mul_f32_e32 v3, v4, v0
	v_mul_f32_e32 v3, v3, v236
	v_mul_f32_e32 v4, v5, v0
	v_mul_f32_e32 v4, v4, v237
	v_cvt_pk_bf16_f32 v3, v3, v4
	v_mul_f32_e32 v4, v6, v0
	v_mul_f32_e32 v5, v7, v0
	v_mul_f32_e32 v6, v9, v0
	s_waitcnt vmcnt(2)
	v_mul_f32_e32 v4, v4, v238
	v_mul_f32_e32 v5, v5, v239
	v_cvt_pk_bf16_f32 v4, v4, v5
	v_mul_f32_e32 v5, v8, v0
	v_mul_f32_e32 v5, v5, v240
	v_mul_f32_e32 v6, v6, v241
	v_cvt_pk_bf16_f32 v5, v5, v6
	s_nop 1
	v_permlane32_swap_b32_e32 v2, v4
	v_permlane32_swap_b32_e32 v3, v5
	s_waitcnt vmcnt(1)
	v_mul_f32_e32 v6, v10, v98
	v_mul_f32_e32 v10, v11, v0
	v_mul_f32_e32 v7, v10, v99
	v_cvt_pk_bf16_f32 v6, v6, v7
	v_mul_f32_e32 v7, v12, v0
	v_mul_f32_e32 v7, v7, v100
	v_mul_f32_e32 v8, v13, v0
	v_mul_f32_e32 v8, v8, v101
	v_cvt_pk_bf16_f32 v7, v7, v8
	v_mul_f32_e32 v12, v14, v0
	s_waitcnt vmcnt(0)
	v_mul_f32_e32 v8, v12, v102
	v_mul_f32_e32 v12, v15, v0
	v_mul_f32_e32 v9, v12, v103
	v_cvt_pk_bf16_f32 v8, v8, v9
	v_mul_f32_e32 v9, v16, v0
	v_mul_f32_e32 v0, v17, v0
	v_mul_f32_e32 v9, v9, v104
	v_mul_f32_e32 v0, v0, v105
	v_lshlrev_b64 v[10:11], 12, v[164:165]
	v_lshl_add_u64 v[10:11], s[2:3], 0, v[10:11]
	v_cvt_pk_bf16_f32 v9, v9, v0
	v_lshl_add_u64 v[10:11], v[10:11], 0, s[72:73]
	v_lshl_add_u64 v[10:11], v[162:163], 1, v[10:11]
	s_nop 1
	v_permlane32_swap_b32_e32 v6, v8
	v_permlane32_swap_b32_e32 v7, v9
	global_store_dwordx4 v[10:11], v[50:53], off
	global_store_dwordx4 v[10:11], v[54:57], off offset:32
	global_store_dwordx4 v[10:11], v[34:37], off offset:64
	global_store_dwordx4 v[10:11], v[38:41], off offset:96
	global_store_dwordx4 v[10:11], v[18:21], off offset:128
	global_store_dwordx4 v[10:11], v[22:25], off offset:160
	global_store_dwordx4 v[10:11], v[2:5], off offset:192
	global_store_dwordx4 v[10:11], v[6:9], off offset:224
	v_mbcnt_lo_u32_b32 v152, -1, 0
	v_mbcnt_hi_u32_b32 v152, -1, v152
	v_mov_b32_e32 v163, s79
	v_and_b32_e32 v5, 31, v152
	v_lshl_or_b32 v6, s4, 5, v5
	v_ashrrev_i32_e32 v71, 4, v152
	v_or_b32_e32 v162, s78, v6
	v_mov_b64_e32 v[2:3], s[0:1]
	v_and_b32_e32 v153, 15, v152
	v_mul_lo_u32 v0, v71, s5
	v_ashrrev_i32_e32 v4, 5, v152
	v_mad_u64_u32 v[2:3], s[0:1], v162, s5, v[2:3]
	v_lshl_or_b32 v0, v153, 4, v0
	v_mad_i32_i24 v3, s79, v247, v3
	v_lshlrev_b32_e32 v164, 3, v4
	v_lshl_add_u64 v[204:205], s[76:77], 0, v[0:1]
	v_lshl_add_u64 v[2:3], v[2:3], 0, s[72:73]
	v_ashrrev_i32_e32 v165, 31, v164
	v_add_co_u32_e32 v10, vcc, s25, v204
	v_lshl_add_u64 v[2:3], v[164:165], 1, v[2:3]
	v_lshlrev_b32_e32 v166, 2, v4
	v_addc_co_u32_e32 v11, vcc, 0, v205, vcc
	global_load_dwordx4 v[98:101], v[2:3], off
	global_load_dwordx4 v[102:105], v[2:3], off offset:32
	global_load_dwordx4 v[106:109], v[2:3], off offset:64
	global_load_dwordx4 v[110:113], v[2:3], off offset:96
	global_load_dwordx4 v[114:117], v[2:3], off offset:128
	global_load_dwordx4 v[118:121], v[2:3], off offset:160
	global_load_dwordx4 v[122:125], v[2:3], off offset:192
	global_load_dwordx4 v[126:129], v[2:3], off offset:224
	v_lshlrev_b32_e32 v3, 4, v4
	v_sub_u32_e32 v4, v6, v166
	v_add_co_u32_e32 v14, vcc, s24, v204
	v_cvt_f32_i32_e32 v4, v4
	s_nop 0
	v_addc_co_u32_e32 v15, vcc, 0, v205, vcc
	v_add_co_u32_e32 v18, vcc, s30, v204
	v_mov_b32_e32 v7, s14
	s_nop 0
	v_addc_co_u32_e32 v19, vcc, 0, v205, vcc
	s_mov_b64 s[0:1], 0xc000
	v_add_co_u32_e32 v22, vcc, s10, v204
	v_mad_u32_u24 v2, v5, s26, v7
	v_mul_f32_e64 v70, -v169, v4
	v_mad_u32_u24 v4, v5, s27, v7
	global_load_dwordx4 v[6:9], v0, s[76:77]
	v_lshl_add_u64 v[132:133], v[204:205], 0, s[0:1]
	s_mov_b64 s[0:1], 0x18000
	v_addc_co_u32_e32 v23, vcc, 0, v205, vcc
	global_load_dwordx4 v[10:13], v[10:11], off
	v_lshl_add_u64 v[134:135], v[204:205], 0, s[0:1]
	s_mov_b64 s[0:1], 0x24000
	v_add_co_u32_e32 v26, vcc, s31, v204
; #define LAS __attribute__((address_space(3)))
; __device__ __forceinline__ void diff_task(const bf16_t* proj, bf16_t* xo, int b, int h, int qb, float lam, float post, const float* g_diff, int  , LAS unsigned char* vl) {
;     ...
;     bf16x8 kf[8]; u32x4 kr[8];
;     float sh = 0.f;
;     {
;         u32x4 krb[8];
;         const LAS unsigned char* klaneB = vl + r32 * VROWB + 16 * hi;
;         load_v(kr, kcol, 1, voff);
;         load_v(krb, kcol + (size_t)((qb >= 1 ? 1 : 0) * 32) * NIN, 1, voff);
;         store_k(kl, kr, lane); store_v(vl, krb, lane);
	global_load_dwordx4 v[14:17], v[14:15], off
	v_lshl_add_u64 v[136:137], v[204:205], 0, s[0:1]
	s_mov_b64 s[0:1], 0x30000
	v_addc_co_u32_e32 v27, vcc, 0, v205, vcc
	global_load_dwordx4 v[18:21], v[18:19], off
	v_lshl_add_u64 v[138:139], v[204:205], 0, s[0:1]
	s_mov_b64 s[0:1], 0x3c000
	v_add_co_u32_e32 v30, vcc, s33, v204
	global_load_dwordx4 v[22:25], v[22:23], off
	v_lshl_add_u64 v[140:141], v[204:205], 0, s[0:1]
	s_mov_b64 s[0:1], 0x48000
	v_addc_co_u32_e32 v31, vcc, 0, v205, vcc
	global_load_dwordx4 v[26:29], v[26:27], off
	v_lshl_add_u64 v[142:143], v[204:205], 0, s[0:1]
	s_mov_b64 s[0:1], 0x54000
	v_add_co_u32_e32 v34, vcc, s34, v204
	global_load_dwordx4 v[30:33], v[30:31], off
	v_lshl_add_u64 v[144:145], v[204:205], 0, s[0:1]
	v_addc_co_u32_e32 v35, vcc, 0, v205, vcc
	s_mov_b32 s0, 0x60000
	global_load_dwordx4 v[34:37], v[34:35], off
	v_add_co_u32_e32 v38, vcc, s0, v204
	s_mov_b32 s0, 0x6c000
	s_nop 0
	v_addc_co_u32_e32 v39, vcc, 0, v205, vcc
	v_add_co_u32_e32 v42, vcc, s0, v204
	s_mov_b32 s0, 0x78000
	s_nop 0
	v_addc_co_u32_e32 v43, vcc, 0, v205, vcc
	v_add_co_u32_e32 v46, vcc, s0, v204
	s_mov_b32 s0, 0x84000
	s_nop 0
	v_addc_co_u32_e32 v47, vcc, 0, v205, vcc
	v_add_co_u32_e32 v50, vcc, s0, v204
	s_mov_b32 s0, 0x90000
	s_nop 0
	v_addc_co_u32_e32 v51, vcc, 0, v205, vcc
	v_add_co_u32_e32 v54, vcc, s0, v204
	global_load_dwordx4 v[38:41], v[38:39], off
	s_nop 0
	v_addc_co_u32_e32 v55, vcc, 0, v205, vcc
	s_mov_b32 s0, 0x9c000
	global_load_dwordx4 v[42:45], v[42:43], off
	v_add_co_u32_e32 v58, vcc, s0, v204
	global_load_dwordx4 v[46:49], v[46:47], off
	s_nop 0
	v_addc_co_u32_e32 v59, vcc, 0, v205, vcc
	s_mov_b32 s0, 0xa8000
	global_load_dwordx4 v[50:53], v[50:51], off
	v_add_co_u32_e32 v62, vcc, s0, v204
	global_load_dwordx4 v[54:57], v[54:55], off
	s_nop 0
	v_addc_co_u32_e32 v63, vcc, 0, v205, vcc
	s_mov_b32 s0, 0xb4000
	global_load_dwordx4 v[58:61], v[58:59], off
	v_add_co_u32_e32 v66, vcc, s0, v204
	global_load_dwordx4 v[62:65], v[62:63], off
	s_nop 0
	v_addc_co_u32_e32 v67, vcc, 0, v205, vcc
	global_load_dwordx4 v[66:69], v[66:67], off
	v_lshlrev_b32_e32 v72, 4, v152
	v_and_b32_e32 v72, 0xf0, v72
	v_add_u32_e32 v72, s14, v72
	v_mul_lo_u32 v73, v71, s26
	v_add_u32_e32 v167, v72, v73
	s_waitcnt vmcnt(15)
	ds_write_b128 v167, v[6:9] offset:10240
	s_waitcnt vmcnt(14)
	ds_write_b128 v167, v[10:13] offset:11328
	s_waitcnt vmcnt(13)
	ds_write_b128 v167, v[14:17] offset:12416
	s_waitcnt vmcnt(12)
	ds_write_b128 v167, v[18:21] offset:13504
	s_waitcnt vmcnt(11)
	ds_write_b128 v167, v[22:25] offset:14592
	s_waitcnt vmcnt(10)
	ds_write_b128 v167, v[26:29] offset:15680
	s_waitcnt vmcnt(9)
	ds_write_b128 v167, v[30:33] offset:16768
	s_waitcnt vmcnt(8)
	ds_write_b128 v167, v[34:37] offset:17856
	v_mul_lo_u32 v6, v71, s27
	v_add_u32_e32 v210, v72, v6
	v_or_b32_e32 v6, 2, v166
	v_cmp_gt_i32_e64 s[44:45], v6, v5
	v_or_b32_e32 v6, 3, v166
	v_cmp_gt_i32_e64 s[46:47], v6, v5
	v_add_u32_e32 v6, 8, v166
	v_cmp_gt_i32_e64 s[48:49], v6, v5
	v_add_u32_e32 v6, 9, v166
	v_cmp_gt_i32_e64 s[50:51], v6, v5
	v_add_u32_e32 v6, 10, v166
	v_cmp_gt_i32_e64 s[52:53], v6, v5
	v_add_u32_e32 v6, 11, v166
	v_cmp_gt_i32_e64 s[54:55], v6, v5
	v_add_u32_e32 v6, 16, v166
	v_cmp_gt_i32_e64 s[56:57], v6, v5
	v_add_u32_e32 v6, 17, v166
	v_cmp_gt_i32_e64 s[58:59], v6, v5
	v_add_u32_e32 v6, 18, v166
	v_cmp_gt_i32_e64 s[60:61], v6, v5
	v_add_u32_e32 v6, 19, v166
	v_cmp_gt_i32_e64 s[62:63], v6, v5
	v_add_u32_e32 v6, 24, v166
	v_cmp_gt_i32_e64 s[64:65], v6, v5
	v_add_u32_e32 v6, 25, v166
	v_cmp_gt_i32_e64 s[66:67], v6, v5
	v_add_u32_e32 v6, 26, v166
	v_cmp_gt_i32_e64 s[68:69], v6, v5
	v_add_u32_e32 v6, 27, v166
	s_mov_b32 s3, 0
	v_pk_add_f32 v[168:169], v[168:169], v[70:71] op_sel_hi:[1,0]
	v_pk_add_f32 v[170:171], v[170:171], v[70:71] op_sel_hi:[1,0]
	v_pk_add_f32 v[172:173], v[172:173], v[70:71] op_sel_hi:[1,0]
	v_pk_add_f32 v[174:175], v[174:175], v[70:71] op_sel_hi:[1,0]
	v_pk_add_f32 v[176:177], v[176:177], v[70:71] op_sel_hi:[1,0]
	v_pk_add_f32 v[198:199], v[198:199], v[70:71] op_sel_hi:[1,0]
	v_pk_add_f32 v[200:201], v[200:201], v[70:71] op_sel_hi:[1,0]
	v_pk_add_f32 v[202:203], v[202:203], v[70:71] op_sel_hi:[1,0]
	v_cmp_gt_i32_e64 s[38:39], v166, v5
	v_cmp_lt_i32_e64 s[42:43], v166, v5
	v_cmp_gt_i32_e64 s[70:71], v6, v5
	s_add_i32 s2, s4, -1
	v_add_u32_e32 v154, v4, v3
	v_add_u32_e32 v211, v2, v3
	s_waitcnt vmcnt(7)
	ds_write_b128 v210, v[38:41]
	s_waitcnt vmcnt(6)
	ds_write_b128 v210, v[42:45] offset:1280
	s_waitcnt vmcnt(5)
	ds_write_b128 v210, v[46:49] offset:2560
	s_waitcnt vmcnt(4)
	ds_write_b128 v210, v[50:53] offset:3840
	s_waitcnt vmcnt(3)
	ds_write_b128 v210, v[54:57] offset:5120
	s_waitcnt vmcnt(2)
	ds_write_b128 v210, v[58:61] offset:6400
	s_waitcnt vmcnt(1)
	ds_write_b128 v210, v[62:65] offset:7680
	s_waitcnt vmcnt(0)
	ds_write_b128 v210, v[66:69] offset:8960

; #define LAS __attribute__((address_space(3)))
; __device__ __forceinline__ float sx(float v, int mask, int lane) { return __int_as_float(__builtin_amdgcn_ds_bpermute((lane ^ mask) << 2, __float_as_int(v))); }
; __device__ __forceinline__ void diff_task(const bf16_t* proj, bf16_t* xo, int b, int h, int qb, float lam, float post, const float* g_diff, int  , LAS unsigned char* vl) {
;     ...
;     { const float mo0 = sx(m0, 32, lane), lo0 = sx(l0, 32, lane), mo1 = sx(m1, 32, lane), lo1 = sx(l1, 32, lane);
;       const float M0 = fmaxf(m0, mo0), M1 = fmaxf(m1, mo1);
;       l0 = l0 * __builtin_amdgcn_exp2f(m0 - M0) + lo0 * __builtin_amdgcn_exp2f(mo0 - M0); l1 = l1 * __builtin_amdgcn_exp2f(m1 - M1) + lo1 * __builtin_amdgcn_exp2f(mo1 - M1); m0 = M0; m1 = M1; }
;     const float i0 = 1.0f / l0, i1 = lam / l1;
;     f32x16 ot[4];
; #pragma unroll
;     for (int db = 0; db < 4; ++db) ot[db] = (f32x16){};
;     const int g = lane >> 4, ii = lane & 15;
;     const LAS unsigned char* vtb = vl + (4 * (g >> 1) + (ii >> 2)) * VROWB + (16 * (g & 1) + 4 * (ii & 3)) * 2;
;     u32x4 vr[8];
;     load_v(vr, vcol, 1, voff);
;     load_v(kr, kcol, 1, voff);
;     store_v(vl, vr, lane);
;     store_k(kl, kr, lane);
;     sh = 0.f;
.LBB0_338:
	v_lshlrev_b32_e32 v8, 2, v152
	v_xor_b32_e32 v212, 0x80, v8
	ds_bpermute_b32 v5, v212, v155
	ds_bpermute_b32 v7, v212, v156
	v_max_f32_e32 v6, v155, v155
	ds_bpermute_b32 v2, v212, v130
	ds_bpermute_b32 v3, v212, v131
	s_waitcnt lgkmcnt(3)
	v_max_f32_e32 v4, v5, v5
	v_max_f32_e32 v213, v6, v4
	s_waitcnt lgkmcnt(2)
	v_max_f32_e32 v4, v7, v7
	v_max_f32_e32 v6, v156, v156
	v_max_f32_e32 v214, v6, v4
	v_sub_f32_e32 v5, v5, v213
	v_sub_f32_e32 v7, v7, v214
	v_sub_f32_e32 v4, v155, v213
	v_exp_f32_e32 v6, v5
	v_sub_f32_e32 v5, v156, v214
	v_exp_f32_e32 v7, v7
	v_exp_f32_e32 v4, v4
	v_exp_f32_e32 v5, v5
	v_lshl_add_u64 v[208:209], s[74:75], 0, v[0:1]
	s_waitcnt lgkmcnt(0)
	v_pk_mul_f32 v[2:3], v[6:7], v[2:3]
	v_readlane_b32 s74, v254, 28
	v_pk_fma_f32 v[2:3], v[146:147], v[4:5], v[2:3]
	v_mov_b32_e32 v0, 0
	v_div_scale_f32 v4, s[0:1], v3, v3, s6
	v_rcp_f32_e32 v5, v4
	v_readlane_b32 s75, v254, 29
	v_fma_f32 v6, -v4, v5, 1.0
	v_fmac_f32_e32 v5, v6, v5
	v_div_scale_f32 v6, vcc, s6, v3, s6
	v_mul_f32_e32 v7, v6, v5
	v_fma_f32 v9, -v4, v7, v6
	v_fmac_f32_e32 v7, v9, v5
	v_fma_f32 v4, -v4, v7, v6
	v_div_fmas_f32 v4, v4, v5, v7
	v_div_fixup_f32 v207, v4, v3, s6
	v_div_scale_f32 v3, s[0:1], v2, v2, 1.0
	v_rcp_f32_e32 v4, v3
	s_mov_b32 s0, 0
	s_or_b32 s1, s4, 7
	s_add_i32 s1, s1, 1
	v_fma_f32 v5, -v3, v4, 1.0
	v_fmac_f32_e32 v4, v5, v4
	v_div_scale_f32 v5, vcc, 1.0, v2, 1.0
	v_mul_f32_e32 v6, v5, v4
	v_fma_f32 v7, -v3, v6, v5
	v_fmac_f32_e32 v6, v7, v4
	v_fma_f32 v3, -v3, v6, v5
	v_div_fmas_f32 v3, v3, v4, v6
	v_add_co_u32_e32 v6, vcc, s25, v208
	v_div_fixup_f32 v206, v3, v2, 1.0
	s_nop 0
	v_addc_co_u32_e32 v7, vcc, 0, v209, vcc
	v_add_co_u32_e32 v10, vcc, s24, v208
	v_lshrrev_b32_e32 v2, 3, v152
	s_nop 0
	v_addc_co_u32_e32 v11, vcc, 0, v209, vcc
	v_add_co_u32_e32 v14, vcc, s30, v208
	v_lshrrev_b32_e32 v3, 2, v153
	s_nop 0
	v_addc_co_u32_e32 v15, vcc, 0, v209, vcc
	v_add_co_u32_e32 v18, vcc, s10, v208
	v_and_or_b32 v2, v2, s35, v3
	s_nop 0
	v_addc_co_u32_e32 v19, vcc, 0, v209, vcc
	v_add_co_u32_e32 v22, vcc, s31, v208
	v_mul_lo_u32 v2, v2, s27
	s_nop 0
	v_addc_co_u32_e32 v23, vcc, 0, v209, vcc
	v_add_co_u32_e32 v26, vcc, s33, v208
	v_add_u32_e32 v66, s14, v2
	s_nop 0
	v_addc_co_u32_e32 v27, vcc, 0, v209, vcc
	v_and_b32_e32 v2, 16, v152
	v_add_co_u32_e32 v30, vcc, s34, v208
	v_and_or_b32 v2, v8, 12, v2
	s_nop 0
	v_addc_co_u32_e32 v31, vcc, 0, v209, vcc
	v_lshlrev_b32_e32 v67, 1, v2
	global_load_dwordx4 v[2:5], v[208:209], off
	v_add_u32_e32 v215, v66, v67
	global_load_dwordx4 v[6:9], v[6:7], off
	s_nop 0
	global_load_dwordx4 v[10:13], v[10:11], off
	s_nop 0
	global_load_dwordx4 v[14:17], v[14:15], off
	s_nop 0
	global_load_dwordx4 v[18:21], v[18:19], off
	s_nop 0
	global_load_dwordx4 v[22:25], v[22:23], off
	s_nop 0
	global_load_dwordx4 v[26:29], v[26:27], off
	s_nop 0
	global_load_dwordx4 v[30:33], v[30:31], off
	s_nop 0
	global_load_dwordx4 v[34:37], v[204:205], off
	global_load_dwordx4 v[38:41], v[132:133], off
	global_load_dwordx4 v[42:45], v[134:135], off
	global_load_dwordx4 v[46:49], v[136:137], off
	global_load_dwordx4 v[50:53], v[138:139], off
	global_load_dwordx4 v[54:57], v[140:141], off
	global_load_dwordx4 v[58:61], v[142:143], off
	global_load_dwordx4 v[62:65], v[144:145], off
	s_waitcnt vmcnt(15)
	ds_write_b128 v210, v[2:5]
	s_waitcnt vmcnt(14)
	ds_write_b128 v210, v[6:9] offset:1280
	s_waitcnt vmcnt(13)
	ds_write_b128 v210, v[10:13] offset:2560
	s_waitcnt vmcnt(12)
	ds_write_b128 v210, v[14:17] offset:3840
	s_waitcnt vmcnt(11)
	ds_write_b128 v210, v[18:21] offset:5120
	s_waitcnt vmcnt(10)
	ds_write_b128 v210, v[22:25] offset:6400
	s_waitcnt vmcnt(9)
	ds_write_b128 v210, v[26:29] offset:7680
	s_waitcnt vmcnt(8)
	ds_write_b128 v210, v[30:33] offset:8960
	s_waitcnt vmcnt(7)
	ds_write_b128 v167, v[34:37] offset:10240
	s_waitcnt vmcnt(6)
	ds_write_b128 v167, v[38:41] offset:11328
	s_waitcnt vmcnt(5)
	ds_write_b128 v167, v[42:45] offset:12416
	s_waitcnt vmcnt(4)
	ds_write_b128 v167, v[46:49] offset:13504
	s_waitcnt vmcnt(3)
	ds_write_b128 v167, v[50:53] offset:14592
	s_waitcnt vmcnt(2)
	ds_write_b128 v167, v[54:57] offset:15680
	s_waitcnt vmcnt(1)
	ds_write_b128 v167, v[58:61] offset:16768
	s_waitcnt vmcnt(0)
	ds_write_b128 v167, v[62:65] offset:17856
	v_mov_b32_e32 v2, 0
	v_mov_b32_e32 v3, 0
	v_mov_b32_e32 v4, 0
	v_mov_b32_e32 v5, 0
	v_mov_b32_e32 v6, 0
	v_mov_b32_e32 v7, 0
	v_mov_b32_e32 v8, 0
	v_mov_b32_e32 v9, 0
	v_mov_b32_e32 v10, 0
	v_mov_b32_e32 v11, 0
	v_mov_b32_e32 v12, 0
	v_mov_b32_e32 v13, 0
	v_mov_b32_e32 v14, 0
	v_mov_b32_e32 v15, 0
	v_mov_b32_e32 v16, 0
	v_mov_b32_e32 v17, 0
	v_mov_b32_e32 v18, 0
	v_mov_b32_e32 v19, 0
	v_mov_b32_e32 v20, 0
	v_mov_b32_e32 v21, 0
	v_mov_b32_e32 v22, 0
	v_mov_b32_e32 v23, 0
	v_mov_b32_e32 v24, 0
	v_mov_b32_e32 v25, 0
	v_mov_b32_e32 v26, 0
	v_mov_b32_e32 v27, 0
	v_mov_b32_e32 v28, 0
	v_mov_b32_e32 v29, 0
	v_mov_b32_e32 v30, 0
	v_mov_b32_e32 v31, 0
	v_mov_b32_e32 v32, 0
	v_mov_b32_e32 v33, 0
	v_mov_b32_e32 v34, 0
	v_mov_b32_e32 v35, 0
	v_mov_b32_e32 v36, 0
	v_mov_b32_e32 v37, 0
	v_mov_b32_e32 v38, 0
	v_mov_b32_e32 v39, 0
	v_mov_b32_e32 v40, 0
	v_mov_b32_e32 v41, 0
	v_mov_b32_e32 v42, 0
	v_mov_b32_e32 v43, 0
	v_mov_b32_e32 v44, 0
	v_mov_b32_e32 v45, 0
	v_mov_b32_e32 v46, 0
	v_mov_b32_e32 v47, 0
	v_mov_b32_e32 v48, 0
	v_mov_b32_e32 v49, 0
	v_mov_b32_e32 v50, 0
	v_mov_b32_e32 v51, 0
	v_mov_b32_e32 v52, 0
	v_mov_b32_e32 v53, 0
	v_mov_b32_e32 v54, 0
	v_mov_b32_e32 v55, 0
	v_mov_b32_e32 v56, 0
	v_mov_b32_e32 v57, 0
	v_mov_b32_e32 v58, 0
	v_mov_b32_e32 v59, 0
	v_mov_b32_e32 v60, 0
	v_mov_b32_e32 v61, 0
	v_mov_b32_e32 v62, 0
	v_mov_b32_e32 v63, 0
	v_mov_b32_e32 v64, 0
	v_mov_b32_e32 v65, 0
	s_and_b32 s80, s7, 7
	s_mul_i32 s81, s80, 0xc000
	s_mul_i32 s82, s80, 0x45c0
	s_mul_i32 s83, s80, 0x4500
	v_subrev_u32_e32 v154, s82, v167
	v_add_u32_e32 v155, 0xde00, v154
	v_add_u32_e32 v156, 0x1bc00, v154
	v_subrev_u32_e32 v157, s83, v210
	v_add_u32_e32 v160, 0x12800, v157
	s_branch .LBB0_340
; #define LAS __attribute__((address_space(3)))
; #define MFMA32(a, b, c) __builtin_amdgcn_mfma_f32_32x32x16_bf16((a), (b), (c), 0, 0, 0)
; __device__ __forceinline__ s16x4 vtr(const LAS unsigned char* p) { return __builtin_bit_cast(s16x4, __builtin_amdgcn_ds_read_tr16_b64_v4i16((LAS s16x4*)p)); }
; __device__ __forceinline__ void pv_chunk(f32x16 (&ot)[4], const LAS unsigned char* vtb, bf16x8 pf0, bf16x8 pf1) {
; #pragma unroll
;     for (int db = 0; db < 4; ++db)
; #pragma unroll
;         for (int s = 0; s < 2; ++s) {
;             const s16x4 a = vtr(vtb + (16 * s) * VROWB + 64 * db), b2 = vtr(vtb + (16 * s + 8) * VROWB + 64 * db);
;             const bf16x8 vf = (bf16x8){a[0], a[1], a[2], a[3], b2[0], b2[1], b2[2], b2[3]};
;             __builtin_amdgcn_s_setprio(1); ot[db] = MFMA32(vf, s ? pf1 : pf0, ot[db]); __builtin_amdgcn_s_setprio(0);
;         }
; }
; __device__ __forceinline__ void diff_task(const bf16_t* proj, bf16_t* xo, int b, int h, int qb, float lam, float post, const float* g_diff, int  , LAS unsigned char* vl) {
;     ...
;         const float e0 = m0 - sh, e1 = m1 - sh;
;         float p[16];
; #pragma unroll
;         for (int r = 0; r < 16; ++r) { const float bq0 = B0(r) - e0, bq1 = B0(r) - e1; p[r] = __builtin_amdgcn_exp2f(s0[r] * c1 + bq0) * i0 - __builtin_amdgcn_exp2f(s1[r] * c1 + bq1) * i1; }
;         bf16x8 pf0 = pack8(p), pf1 = pack8(p + 8);
;         asm volatile("" : "+v"(pf0), "+v"(pf1));
;         load_v(vr, vcol + (size_t)(kn * 32) * NIN, 1, voff);
;         pv_chunk(ot, vtb, pf0, pf1);
;         store_k(kl, kr, lane);
;         store_v(vl, vr, lane);
;         sh += c2s;
.LBB0_339:
	ds_read_b64_tr_b16 v[134:135], v215
	ds_read_b64_tr_b16 v[136:137], v215 offset:2560
	ds_read_b64_tr_b16 v[138:139], v215 offset:5120
	ds_read_b64_tr_b16 v[140:141], v215 offset:7680
	ds_read_b64_tr_b16 v[142:143], v215 offset:64
	ds_read_b64_tr_b16 v[144:145], v215 offset:2624
	ds_read_b64_tr_b16 v[146:147], v215 offset:5184
	ds_read_b64_tr_b16 v[148:149], v215 offset:7744
	ds_read_b64_tr_b16 v[150:151], v215 offset:128
	ds_read_b64_tr_b16 v[152:153], v215 offset:2688
	v_sub_f32_e32 v186, v213, v0
	v_sub_f32_e32 v187, v214, v0
	v_sub_f32_e32 v184, v168, v186
	v_sub_f32_e32 v185, v168, v187
	v_fmac_f32_e32 v184, 0x3e38aa3b, v82
	v_fmac_f32_e32 v185, 0x3e38aa3b, v66
	v_exp_f32_e32 v184, v184
	v_exp_f32_e32 v185, v185
	v_sub_f32_e32 v82, v169, v187
	v_sub_f32_e32 v66, v169, v186
	v_fmac_f32_e32 v82, 0x3e38aa3b, v67
	v_fmac_f32_e32 v66, 0x3e38aa3b, v83
	v_exp_f32_e32 v67, v82
	v_pk_mul_f32 v[82:83], v[206:207], v[184:185]
	v_exp_f32_e32 v66, v66
	v_sub_f32_e32 v184, v82, v83
	v_sub_f32_e32 v82, v170, v186
	v_sub_f32_e32 v83, v170, v187
	v_fmac_f32_e32 v82, 0x3e38aa3b, v84
	v_fmac_f32_e32 v83, 0x3e38aa3b, v68
	v_sub_f32_e32 v68, v171, v186
	v_sub_f32_e32 v84, v171, v187
	v_exp_f32_e32 v82, v82
	v_exp_f32_e32 v83, v83
	v_fmac_f32_e32 v68, 0x3e38aa3b, v85
	v_fmac_f32_e32 v84, 0x3e38aa3b, v69
	v_exp_f32_e32 v68, v68
	v_exp_f32_e32 v69, v84
	v_pk_mul_f32 v[66:67], v[206:207], v[66:67]
	s_nop 0
	v_sub_f32_e32 v84, v66, v67
	v_pk_mul_f32 v[66:67], v[206:207], v[82:83]
	v_sub_f32_e32 v83, v173, v187
	v_sub_f32_e32 v82, v66, v67
	v_pk_mul_f32 v[66:67], v[206:207], v[68:69]
	v_sub_f32_e32 v68, v172, v186
	v_sub_f32_e32 v69, v172, v187
	v_fmac_f32_e32 v68, 0x3e38aa3b, v86
	v_fmac_f32_e32 v69, 0x3e38aa3b, v70
	v_sub_f32_e32 v70, v173, v186
	v_exp_f32_e32 v68, v68
	v_exp_f32_e32 v69, v69
	v_fmac_f32_e32 v70, 0x3e38aa3b, v87
	v_fmac_f32_e32 v83, 0x3e38aa3b, v71
	v_exp_f32_e32 v70, v70
	v_exp_f32_e32 v71, v83
	v_sub_f32_e32 v83, v66, v67
	v_pk_mul_f32 v[66:67], v[206:207], v[68:69]
	v_sub_f32_e32 v68, v174, v186
	v_sub_f32_e32 v69, v174, v187
	v_sub_f32_e32 v85, v66, v67
	v_pk_mul_f32 v[66:67], v[206:207], v[70:71]
	v_fmac_f32_e32 v68, 0x3e38aa3b, v88
	v_fmac_f32_e32 v69, 0x3e38aa3b, v72
	v_sub_f32_e32 v70, v175, v186
	v_sub_f32_e32 v71, v175, v187
	v_exp_f32_e32 v68, v68
	v_exp_f32_e32 v69, v69
	v_fmac_f32_e32 v70, 0x3e38aa3b, v89
	v_fmac_f32_e32 v71, 0x3e38aa3b, v73
	v_exp_f32_e32 v70, v70
	v_exp_f32_e32 v71, v71
	v_sub_f32_e32 v72, v66, v67
	v_pk_mul_f32 v[66:67], v[206:207], v[68:69]
	v_sub_f32_e32 v68, v176, v186
	v_sub_f32_e32 v69, v176, v187
	v_sub_f32_e32 v73, v66, v67
	v_pk_mul_f32 v[66:67], v[206:207], v[70:71]
	v_fmac_f32_e32 v68, 0x3e38aa3b, v90
	v_fmac_f32_e32 v69, 0x3e38aa3b, v74
	v_sub_f32_e32 v70, v177, v186
	v_sub_f32_e32 v71, v177, v187
	v_exp_f32_e32 v68, v68
	v_exp_f32_e32 v69, v69
	v_fmac_f32_e32 v70, 0x3e38aa3b, v91
	v_fmac_f32_e32 v71, 0x3e38aa3b, v75
	v_exp_f32_e32 v70, v70
	v_exp_f32_e32 v71, v71
	v_sub_f32_e32 v74, v66, v67
	v_pk_mul_f32 v[66:67], v[206:207], v[68:69]
	v_sub_f32_e32 v68, v198, v186
	v_sub_f32_e32 v69, v198, v187
	v_sub_f32_e32 v75, v66, v67
	v_pk_mul_f32 v[66:67], v[206:207], v[70:71]
	v_fmac_f32_e32 v68, 0x3e38aa3b, v92
	v_fmac_f32_e32 v69, 0x3e38aa3b, v76
	v_sub_f32_e32 v70, v199, v186
	v_sub_f32_e32 v71, v199, v187
	v_exp_f32_e32 v68, v68
	v_exp_f32_e32 v69, v69
	v_fmac_f32_e32 v70, 0x3e38aa3b, v93
	v_fmac_f32_e32 v71, 0x3e38aa3b, v77
	v_exp_f32_e32 v70, v70
	v_exp_f32_e32 v71, v71
	v_sub_f32_e32 v76, v66, v67
	v_pk_mul_f32 v[66:67], v[206:207], v[68:69]
	v_sub_f32_e32 v68, v200, v186
	v_sub_f32_e32 v69, v200, v187
	v_sub_f32_e32 v77, v66, v67
	v_pk_mul_f32 v[66:67], v[206:207], v[70:71]
	v_fmac_f32_e32 v68, 0x3e38aa3b, v94
	v_fmac_f32_e32 v69, 0x3e38aa3b, v78
	v_sub_f32_e32 v70, v201, v186
	v_sub_f32_e32 v71, v201, v187
	v_exp_f32_e32 v68, v68
	v_exp_f32_e32 v69, v69
	v_fmac_f32_e32 v70, 0x3e38aa3b, v95
	v_fmac_f32_e32 v71, 0x3e38aa3b, v79
	v_exp_f32_e32 v70, v70
	v_exp_f32_e32 v71, v71
	v_sub_f32_e32 v78, v66, v67
	v_pk_mul_f32 v[66:67], v[206:207], v[68:69]
	v_sub_f32_e32 v68, v202, v186
	v_sub_f32_e32 v69, v202, v187
	v_sub_f32_e32 v79, v66, v67
	v_pk_mul_f32 v[66:67], v[206:207], v[70:71]
	v_fmac_f32_e32 v68, 0x3e38aa3b, v96
	v_fmac_f32_e32 v69, 0x3e38aa3b, v80
	v_sub_f32_e32 v70, v203, v186
	v_sub_f32_e32 v71, v203, v187
	v_exp_f32_e32 v68, v68
	v_exp_f32_e32 v69, v69
	v_fmac_f32_e32 v70, 0x3e38aa3b, v97
	v_fmac_f32_e32 v71, 0x3e38aa3b, v81
	v_exp_f32_e32 v70, v70
	v_exp_f32_e32 v71, v71
	v_sub_f32_e32 v80, v66, v67
	v_pk_mul_f32 v[66:67], v[206:207], v[68:69]
	s_nop 0
	v_sub_f32_e32 v81, v66, v67
	v_pk_mul_f32 v[66:67], v[206:207], v[70:71]
	s_nop 0
	v_sub_f32_e32 v86, v66, v67
	v_cvt_pk_bf16_f32 v66, v184, v84
	v_lshl_add_u64 v[184:185], s[2:3], 1, v[208:209]
	v_cvt_pk_bf16_f32 v67, v82, v83
	v_cvt_pk_bf16_f32 v68, v85, v72
	v_cvt_pk_bf16_f32 v69, v73, v74
	v_cvt_pk_bf16_f32 v70, v75, v76
	v_cvt_pk_bf16_f32 v71, v77, v78
	v_cvt_pk_bf16_f32 v72, v79, v80
	v_cvt_pk_bf16_f32 v73, v81, v86
	v_add_co_u32_e32 v184, vcc, s81, v184
	s_nop 1
	v_addc_co_u32_e32 v185, vcc, 0, v185, vcc
	global_load_dwordx4 v[74:77], v[184:185], off
	ds_read_b64_tr_b16 v[78:79], v215 offset:5248
	ds_read_b64_tr_b16 v[80:81], v215 offset:7808
	ds_read_b64_tr_b16 v[82:83], v215 offset:192
	ds_read_b64_tr_b16 v[84:85], v215 offset:2752
	ds_read_b64_tr_b16 v[86:87], v215 offset:5312
	ds_read_b64_tr_b16 v[88:89], v215 offset:7872
	s_setprio 1
	s_waitcnt lgkmcnt(6)
	v_mfma_f32_32x32x16_bf16 v[50:65], v[134:137], v[66:69], v[50:65]
	v_mfma_f32_32x32x16_bf16 v[50:65], v[138:141], v[70:73], v[50:65]
	v_mfma_f32_32x32x16_bf16 v[34:49], v[142:145], v[66:69], v[34:49]
	v_mfma_f32_32x32x16_bf16 v[34:49], v[146:149], v[70:73], v[34:49]
	v_mfma_f32_32x32x16_bf16 v[18:33], v[150:153], v[66:69], v[18:33]
	s_waitcnt lgkmcnt(4)
	v_mfma_f32_32x32x16_bf16 v[18:33], v[78:81], v[70:73], v[18:33]
	s_waitcnt lgkmcnt(2)
	v_mfma_f32_32x32x16_bf16 v[2:17], v[82:85], v[66:69], v[2:17]
	s_waitcnt lgkmcnt(0)
	v_mfma_f32_32x32x16_bf16 v[2:17], v[86:89], v[70:73], v[2:17]
	s_setprio 0
	s_cmp_lg_u32 s1, s0
	v_add_f32_e32 v0, v226, v0
	s_barrier
	s_waitcnt vmcnt(1)
	ds_write_b128 v154, v[130:133] offset:10240
	ds_write_b128 v154, v[130:133] offset:29184
	ds_write_b128 v154, v[130:133] offset:48128
	ds_write_b128 v155, v[130:133] offset:10240
	ds_write_b128 v155, v[130:133] offset:29184
	ds_write_b128 v155, v[130:133] offset:48128
	ds_write_b128 v156, v[130:133] offset:10240
	ds_write_b128 v156, v[130:133] offset:29184
	s_waitcnt vmcnt(0)
	ds_write_b128 v157, v[74:77]
	ds_write_b128 v157, v[74:77] offset:18944
	ds_write_b128 v157, v[74:77] offset:37888
	ds_write_b128 v157, v[74:77] offset:56832
	ds_write_b128 v160, v[74:77]
	ds_write_b128 v160, v[74:77] offset:18944
	ds_write_b128 v160, v[74:77] offset:37888
	ds_write_b128 v160, v[74:77] offset:56832
	s_waitcnt lgkmcnt(0)
	s_barrier
	s_cbranch_scc0 .LBB0_313
; #define MFMA32(a, b, c) __builtin_amdgcn_mfma_f32_32x32x16_bf16((a), (b), (c), 0, 0, 0)
; __device__ __forceinline__ int crow(int r, int hi) { return (r & 3) + 8 * (r >> 2) + 4 * hi; }
; __device__ __forceinline__ void diff_task(const bf16_t* proj, bf16_t* xo, int b, int h, int qb, float lam, float post, const float* g_diff, int  , LAS unsigned char* vl) {
;     ...
;     for (int kc = 0; kc <= qb; ++kc) {
;         read_kf(kf, klane);
;         f32x16 s0 = {}, s1 = {};
; #pragma unroll
;         for (int d0 = 0; d0 < 4; ++d0) { s0 = MFMA32(kf[d0], qf[d0], s0); s1 = MFMA32(kf[4 + d0], qf[4 + d0], s1); }
;         const int kn = kc < qb ? kc + 1 : kc;
;         load_v(kr, kcol + (size_t)(kn * 32) * NIN, 1, voff);
;         if (kc == qb) {
; #pragma unroll
;             for (int r = 0; r < 16; ++r) if (crow(r, hi) > r32) { s0[r] = NEGBIG; s1[r] = NEGBIG; }
;         }
.LBB0_340:
	ds_read_b128 v[66:69], v211 offset:10240
	ds_read_b128 v[130:133], v211 offset:10272
	ds_read_b128 v[134:137], v211 offset:10304
	ds_read_b128 v[138:141], v211 offset:10336
	ds_read_b128 v[70:73], v211 offset:10368
	ds_read_b128 v[142:145], v211 offset:10400
	ds_read_b128 v[146:149], v211 offset:10432
	ds_read_b128 v[150:153], v211 offset:10464
	s_waitcnt lgkmcnt(7)
	v_mfma_f32_32x32x16_bf16 v[82:97], v[66:69], v[98:101], 0
	s_mov_b32 s5, s0
	s_add_i32 s0, s0, 1
	s_cmp_lt_u32 s0, s1
	s_cselect_b32 s2, s0, s5
	s_lshl_b32 s3, s2, 5
	s_mul_i32 s2, s2, 0x30000
	s_mul_hi_u32 s3, s3, 0x1800
	s_waitcnt lgkmcnt(3)
	v_mfma_f32_32x32x16_bf16 v[66:81], v[70:73], v[114:117], 0
	v_lshl_add_u64 v[158:159], s[2:3], 1, v[204:205]
	s_cmp_lg_u32 s4, s5
	v_mfma_f32_32x32x16_bf16 v[82:97], v[130:133], v[102:105], v[82:97]
	v_add_co_u32_e32 v158, vcc, s81, v158
	s_waitcnt lgkmcnt(2)
	v_mfma_f32_32x32x16_bf16 v[66:81], v[142:145], v[118:121], v[66:81]
	v_mfma_f32_32x32x16_bf16 v[82:97], v[134:137], v[106:109], v[82:97]
	v_addc_co_u32_e32 v159, vcc, 0, v159, vcc
	global_load_dwordx4 v[130:133], v[158:159], off
	s_waitcnt lgkmcnt(1)
	v_mfma_f32_32x32x16_bf16 v[66:81], v[146:149], v[122:125], v[66:81]
	v_mfma_f32_32x32x16_bf16 v[82:97], v[138:141], v[110:113], v[82:97]
	s_waitcnt lgkmcnt(0)
	v_mfma_f32_32x32x16_bf16 v[66:81], v[150:153], v[126:129], v[66:81]
	s_nop 7
	s_nop 3
	s_cbranch_scc1 .Lpb2_chk
	v_cndmask_b32_e64 v184, v82, v248, s[38:39]
	v_cndmask_b32_e64 v185, v66, v248, s[38:39]
	v_cndmask_b32_e64 v83, v248, v83, s[42:43]
	v_cndmask_b32_e64 v82, v184, v82, s[42:43]
	v_cndmask_b32_e64 v67, v248, v67, s[42:43]
	v_cndmask_b32_e64 v66, v185, v66, s[42:43]
	v_cndmask_b32_e64 v84, v84, v248, s[44:45]
	v_cndmask_b32_e64 v68, v68, v248, s[44:45]
	v_cndmask_b32_e64 v85, v85, v248, s[46:47]
	v_cndmask_b32_e64 v69, v69, v248, s[46:47]
	v_cndmask_b32_e64 v86, v86, v248, s[48:49]
	v_cndmask_b32_e64 v70, v70, v248, s[48:49]
	v_cndmask_b32_e64 v87, v87, v248, s[50:51]
	v_cndmask_b32_e64 v71, v71, v248, s[50:51]
	v_cndmask_b32_e64 v88, v88, v248, s[52:53]
	v_cndmask_b32_e64 v72, v72, v248, s[52:53]
	v_cndmask_b32_e64 v89, v89, v248, s[54:55]
	v_cndmask_b32_e64 v73, v73, v248, s[54:55]
	v_cndmask_b32_e64 v90, v90, v248, s[56:57]
	v_cndmask_b32_e64 v74, v74, v248, s[56:57]
	v_cndmask_b32_e64 v91, v91, v248, s[58:59]
	v_cndmask_b32_e64 v75, v75, v248, s[58:59]
	v_cndmask_b32_e64 v92, v92, v248, s[60:61]
	v_cndmask_b32_e64 v76, v76, v248, s[60:61]
	v_cndmask_b32_e64 v93, v93, v248, s[62:63]
	v_cndmask_b32_e64 v77, v77, v248, s[62:63]
	v_cndmask_b32_e64 v94, v94, v248, s[64:65]
	v_cndmask_b32_e64 v78, v78, v248, s[64:65]
	v_cndmask_b32_e64 v95, v95, v248, s[66:67]
	v_cndmask_b32_e64 v79, v79, v248, s[66:67]
	v_cndmask_b32_e64 v96, v96, v248, s[68:69]
	v_cndmask_b32_e64 v80, v80, v248, s[68:69]
	v_cndmask_b32_e64 v97, v97, v248, s[70:71]
	v_cndmask_b32_e64 v81, v81, v248, s[70:71]
	s_branch .LBB0_339
.Lpb2_chk:
	s_cmp_gt_u32 s5, s4
	s_cbranch_scc0 .LBB0_339
	v_mov_b32_e32 v66, v248
	v_mov_b32_e32 v67, v248
	v_mov_b32_e32 v68, v248
	v_mov_b32_e32 v69, v248
	v_mov_b32_e32 v70, v248
	v_mov_b32_e32 v71, v248
	v_mov_b32_e32 v72, v248
	v_mov_b32_e32 v73, v248
	v_mov_b32_e32 v74, v248
	v_mov_b32_e32 v75, v248
	v_mov_b32_e32 v76, v248
	v_mov_b32_e32 v77, v248
	v_mov_b32_e32 v78, v248
	v_mov_b32_e32 v79, v248
	v_mov_b32_e32 v80, v248
	v_mov_b32_e32 v81, v248
	v_mov_b32_e32 v82, v248
	v_mov_b32_e32 v83, v248
	v_mov_b32_e32 v84, v248
	v_mov_b32_e32 v85, v248
	v_mov_b32_e32 v86, v248
	v_mov_b32_e32 v87, v248
	v_mov_b32_e32 v88, v248
	v_mov_b32_e32 v89, v248
	v_mov_b32_e32 v90, v248
	v_mov_b32_e32 v91, v248
	v_mov_b32_e32 v92, v248
	v_mov_b32_e32 v93, v248
	v_mov_b32_e32 v94, v248
	v_mov_b32_e32 v95, v248
	v_mov_b32_e32 v96, v248
	v_mov_b32_e32 v97, v248
	s_branch .LBB0_339

; __device__ __forceinline__ unsigned cvt_pk_bf16(float lo, float hi) { unsigned r; asm volatile("v_cvt_pk_bf16_f32 %0, %1, %2" : "=v"(r) : "v"(lo), "v"(hi)); return r; }
;     __device__ __forceinline__ void operator()(f32x4 (&acc)[2][2][4][2], const Unit& u, int wr, int wc, int fr, int fq) const {
;         const int row0 = u.orow + wr * 64 + fr, col0 = u.ocol + wc * 32 + 8 * fq;
;         f32x4 cv[2][2], bv[2][2];
; #pragma unroll
;         for (int bj = 0; bj < 2; ++bj)
; #pragma unroll
;             for (int n = 0; n < 2; ++n) { cv[bj][n] = *(const f32x4*)(cs + col0 + bj * HALF + 4 * n); bv[bj][n] = *(const f32x4*)(bw + col0 + bj * HALF + 4 * n); }
; #pragma unroll
;         for (int ai = 0; ai < 2; ++ai)
; #pragma unroll
;             for (int m = 0; m < 4; ++m) { const int row = row0 + ai * HALF + m * 16; bf16_t* rowp = O + (size_t)row * ldc + col0;
;                 const f32x2 st = *(const f32x2*)(ps + (size_t)row * 2); const float rs = st[1], nm = -st[0] * rs;
; #pragma unroll
;                 for (int bj = 0; bj < 2; ++bj) { const f32x4 v0 = acc[ai][bj][m][0] * rs + (cv[bj][0] * nm + bv[bj][0]), v1 = acc[ai][bj][m][1] * rs + (cv[bj][1] * nm + bv[bj][1]);
;                     u32x4 w; w.x = cvt_pk_bf16(v0[0], v0[1]); w.y = cvt_pk_bf16(v0[2], v0[3]); w.z = cvt_pk_bf16(v1[0], v1[1]); w.w = cvt_pk_bf16(v1[2], v1[3]);
;                     *(u32x4*)(rowp + bj * HALF) = w; } }
.LBB0_620:
	v_add_u32_e32 v164, s1, v170
	v_ashrrev_i32_e32 v165, 31, v164
	v_readlane_b32 s2, v251, 12
	v_lshlrev_b64 v[50:51], 2, v[164:165]
	v_readlane_b32 s3, v251, 13
	v_add_u32_e32 v162, s0, v169
	v_ashrrev_i32_e32 v163, 31, v162
	v_lshl_add_u64 v[58:59], s[2:3], 0, v[50:51]
	v_readlane_b32 s2, v251, 14
	v_readlane_b32 s3, v251, 15
	v_lshl_add_u64 v[176:177], v[162:163], 3, s[70:71]
	v_lshlrev_b64 v[174:175], 12, v[162:163]
	v_lshl_add_u64 v[74:75], s[2:3], 0, v[50:51]
	global_load_dwordx4 v[54:57], v[58:59], off offset:16
	global_load_dwordx4 v[70:73], v[58:59], off
	global_load_dwordx4 v[62:65], v[74:75], off offset:16
	global_load_dwordx4 v[78:81], v[74:75], off
	global_load_dwordx4 v[50:53], v[58:59], off offset:528
	global_load_dwordx4 v[66:69], v[58:59], off offset:512
	s_nop 0
	global_load_dwordx4 v[58:61], v[74:75], off offset:528
	s_nop 0
	global_load_dwordx4 v[74:77], v[74:75], off offset:512
	v_lshl_add_u64 v[174:175], s[74:75], 0, v[174:175]
	global_load_dwordx2 v[230:231], v[176:177], off offset:128
	global_load_dwordx2 v[232:233], v[176:177], off offset:256
	global_load_dwordx2 v[234:235], v[176:177], off offset:384
	global_load_dwordx2 v[236:237], v[176:177], off offset:1024
	global_load_dwordx2 v[238:239], v[176:177], off offset:1152
	global_load_dwordx2 v[240:241], v[176:177], off offset:1280
	global_load_dwordx2 v[196:197], v[176:177], off offset:1408
	global_load_dwordx2 v[176:177], v[176:177], off
	v_lshlrev_b64 v[164:165], 1, v[164:165]
	v_lshl_add_u64 v[174:175], v[174:175], 0, v[164:165]
	s_mov_b64 s[2:3], -1
	s_andn2_b64 vcc, exec, s[44:45]
	s_waitcnt vmcnt(0)
	v_mul_f32_e64 v178, v177, -v176
	v_pk_fma_f32 v[184:185], v[72:73], v[178:179], v[80:81] op_sel_hi:[1, 0, 1]
	v_pk_fma_f32 v[186:187], v[70:71], v[178:179], v[78:79] op_sel_hi:[1, 0, 1]
	v_pk_fma_f32 v[160:161], v[160:161], v[176:177], v[184:185] op_sel:[0, 1, 0]
	v_pk_fma_f32 v[158:159], v[158:159], v[176:177], v[186:187] op_sel:[0, 1, 0]
	v_pk_fma_f32 v[184:185], v[56:57], v[178:179], v[64:65] op_sel_hi:[1, 0, 1]
	v_pk_fma_f32 v[186:187], v[54:55], v[178:179], v[62:63] op_sel_hi:[1, 0, 1]
	v_pk_fma_f32 v[184:185], v[156:157], v[176:177], v[184:185] op_sel:[0, 1, 0]
	v_pk_fma_f32 v[156:157], v[154:155], v[176:177], v[186:187] op_sel:[0, 1, 0]
	v_cvt_pk_bf16_f32 v154, v158, v159
	v_cvt_pk_bf16_f32 v155, v160, v161
	s_nop 0
	v_cvt_pk_bf16_f32 v156, v156, v157
	v_cvt_pk_bf16_f32 v157, v184, v185
	global_store_dwordx4 v[174:175], v[154:157], off
	s_nop 1
	v_pk_fma_f32 v[154:155], v[68:69], v[178:179], v[76:77] op_sel_hi:[1, 0, 1]
	v_pk_fma_f32 v[156:157], v[66:67], v[178:179], v[74:75] op_sel_hi:[1, 0, 1]
	v_pk_fma_f32 v[152:153], v[152:153], v[176:177], v[154:155] op_sel:[0, 1, 0]
	v_pk_fma_f32 v[150:151], v[150:151], v[176:177], v[156:157] op_sel:[0, 1, 0]
	v_pk_fma_f32 v[154:155], v[52:53], v[178:179], v[60:61] op_sel_hi:[1, 0, 1]
	v_pk_fma_f32 v[156:157], v[50:51], v[178:179], v[58:59] op_sel_hi:[1, 0, 1]
	v_pk_fma_f32 v[154:155], v[148:149], v[176:177], v[154:155] op_sel:[0, 1, 0]
	v_pk_fma_f32 v[148:149], v[146:147], v[176:177], v[156:157] op_sel:[0, 1, 0]
	v_cvt_pk_bf16_f32 v146, v150, v151
	v_cvt_pk_bf16_f32 v147, v152, v153
	s_nop 0
	v_cvt_pk_bf16_f32 v148, v148, v149
	v_cvt_pk_bf16_f32 v149, v154, v155
	global_store_dwordx4 v[174:175], v[146:149], off offset:256
	s_nop 1
	v_add_u32_e32 v146, 16, v162
	v_ashrrev_i32_e32 v147, 31, v146
	v_lshlrev_b64 v[148:149], 12, v[146:147]
	v_lshl_add_u64 v[148:149], s[74:75], 0, v[148:149]
	v_lshl_add_u64 v[148:149], v[148:149], 0, v[164:165]
	v_mul_f32_e64 v150, v231, -v230
	v_pk_fma_f32 v[152:153], v[72:73], v[150:151], v[80:81] op_sel_hi:[1, 0, 1]
	v_pk_fma_f32 v[154:155], v[70:71], v[150:151], v[78:79] op_sel_hi:[1, 0, 1]
	v_pk_fma_f32 v[144:145], v[144:145], v[230:231], v[152:153] op_sel:[0, 1, 0]
	v_pk_fma_f32 v[142:143], v[142:143], v[230:231], v[154:155] op_sel:[0, 1, 0]
	v_pk_fma_f32 v[152:153], v[56:57], v[150:151], v[64:65] op_sel_hi:[1, 0, 1]
	v_pk_fma_f32 v[154:155], v[54:55], v[150:151], v[62:63] op_sel_hi:[1, 0, 1]
	v_pk_fma_f32 v[152:153], v[140:141], v[230:231], v[152:153] op_sel:[0, 1, 0]
	v_pk_fma_f32 v[140:141], v[138:139], v[230:231], v[154:155] op_sel:[0, 1, 0]
	v_cvt_pk_bf16_f32 v138, v142, v143
	v_cvt_pk_bf16_f32 v139, v144, v145
	s_nop 0
	v_cvt_pk_bf16_f32 v140, v140, v141
	v_cvt_pk_bf16_f32 v141, v152, v153
	global_store_dwordx4 v[148:149], v[138:141], off
	s_nop 1
	v_pk_fma_f32 v[138:139], v[68:69], v[150:151], v[76:77] op_sel_hi:[1, 0, 1]
	v_pk_fma_f32 v[140:141], v[66:67], v[150:151], v[74:75] op_sel_hi:[1, 0, 1]
	v_pk_fma_f32 v[136:137], v[136:137], v[230:231], v[138:139] op_sel:[0, 1, 0]
	v_pk_fma_f32 v[134:135], v[134:135], v[230:231], v[140:141] op_sel:[0, 1, 0]
	v_pk_fma_f32 v[138:139], v[52:53], v[150:151], v[60:61] op_sel_hi:[1, 0, 1]
	v_pk_fma_f32 v[140:141], v[50:51], v[150:151], v[58:59] op_sel_hi:[1, 0, 1]
	v_pk_fma_f32 v[138:139], v[132:133], v[230:231], v[138:139] op_sel:[0, 1, 0]
	v_pk_fma_f32 v[132:133], v[130:131], v[230:231], v[140:141] op_sel:[0, 1, 0]
	v_cvt_pk_bf16_f32 v130, v134, v135
	v_cvt_pk_bf16_f32 v131, v136, v137
	s_nop 0
	v_cvt_pk_bf16_f32 v132, v132, v133
	v_cvt_pk_bf16_f32 v133, v138, v139
	global_store_dwordx4 v[148:149], v[130:133], off offset:256
	s_nop 1
	v_add_u32_e32 v130, 32, v162
	v_ashrrev_i32_e32 v131, 31, v130
	v_lshlrev_b64 v[132:133], 12, v[130:131]
	v_lshl_add_u64 v[132:133], s[74:75], 0, v[132:133]
	v_lshl_add_u64 v[132:133], v[132:133], 0, v[164:165]
	v_mul_f32_e64 v134, v233, -v232
	v_pk_fma_f32 v[136:137], v[72:73], v[134:135], v[80:81] op_sel_hi:[1, 0, 1]
	v_pk_fma_f32 v[138:139], v[70:71], v[134:135], v[78:79] op_sel_hi:[1, 0, 1]
; __device__ __forceinline__ unsigned cvt_pk_bf16(float lo, float hi) { unsigned r; asm volatile("v_cvt_pk_bf16_f32 %0, %1, %2" : "=v"(r) : "v"(lo), "v"(hi)); return r; }
;     __device__ __forceinline__ void operator()(f32x4 (&acc)[2][2][4][2], const Unit& u, int wr, int wc, int fr, int fq) const {
;     ...
;             for (int m = 0; m < 4; ++m) { const int row = row0 + ai * HALF + m * 16; bf16_t* rowp = O + (size_t)row * ldc + col0;
;                 const f32x2 st = *(const f32x2*)(ps + (size_t)row * 2); const float rs = st[1], nm = -st[0] * rs;
; #pragma unroll
;                 for (int bj = 0; bj < 2; ++bj) { const f32x4 v0 = acc[ai][bj][m][0] * rs + (cv[bj][0] * nm + bv[bj][0]), v1 = acc[ai][bj][m][1] * rs + (cv[bj][1] * nm + bv[bj][1]);
;                     u32x4 w; w.x = cvt_pk_bf16(v0[0], v0[1]); w.y = cvt_pk_bf16(v0[2], v0[3]); w.z = cvt_pk_bf16(v1[0], v1[1]); w.w = cvt_pk_bf16(v1[2], v1[3]);
;                     *(u32x4*)(rowp + bj * HALF) = w; } }
	v_pk_fma_f32 v[128:129], v[128:129], v[232:233], v[136:137] op_sel:[0, 1, 0]
	v_pk_fma_f32 v[126:127], v[126:127], v[232:233], v[138:139] op_sel:[0, 1, 0]
	v_pk_fma_f32 v[136:137], v[56:57], v[134:135], v[64:65] op_sel_hi:[1, 0, 1]
	v_pk_fma_f32 v[138:139], v[54:55], v[134:135], v[62:63] op_sel_hi:[1, 0, 1]
	v_pk_fma_f32 v[136:137], v[124:125], v[232:233], v[136:137] op_sel:[0, 1, 0]
	v_pk_fma_f32 v[124:125], v[122:123], v[232:233], v[138:139] op_sel:[0, 1, 0]
	v_cvt_pk_bf16_f32 v122, v126, v127
	v_cvt_pk_bf16_f32 v123, v128, v129
	s_nop 0
	v_cvt_pk_bf16_f32 v124, v124, v125
	v_cvt_pk_bf16_f32 v125, v136, v137
	global_store_dwordx4 v[132:133], v[122:125], off
	s_nop 1
	v_pk_fma_f32 v[122:123], v[68:69], v[134:135], v[76:77] op_sel_hi:[1, 0, 1]
	v_pk_fma_f32 v[124:125], v[66:67], v[134:135], v[74:75] op_sel_hi:[1, 0, 1]
	v_pk_fma_f32 v[120:121], v[120:121], v[232:233], v[122:123] op_sel:[0, 1, 0]
	v_pk_fma_f32 v[118:119], v[118:119], v[232:233], v[124:125] op_sel:[0, 1, 0]
	v_pk_fma_f32 v[122:123], v[52:53], v[134:135], v[60:61] op_sel_hi:[1, 0, 1]
	v_pk_fma_f32 v[124:125], v[50:51], v[134:135], v[58:59] op_sel_hi:[1, 0, 1]
	v_pk_fma_f32 v[122:123], v[116:117], v[232:233], v[122:123] op_sel:[0, 1, 0]
	v_pk_fma_f32 v[116:117], v[114:115], v[232:233], v[124:125] op_sel:[0, 1, 0]
	v_cvt_pk_bf16_f32 v114, v118, v119
	v_cvt_pk_bf16_f32 v115, v120, v121
	s_nop 0
	v_cvt_pk_bf16_f32 v116, v116, v117
	v_cvt_pk_bf16_f32 v117, v122, v123
	global_store_dwordx4 v[132:133], v[114:117], off offset:256
	s_nop 1
	v_add_u32_e32 v114, 48, v162
	v_ashrrev_i32_e32 v115, 31, v114
	v_lshlrev_b64 v[116:117], 12, v[114:115]
	v_lshl_add_u64 v[116:117], s[74:75], 0, v[116:117]
	v_lshl_add_u64 v[116:117], v[116:117], 0, v[164:165]
	v_mul_f32_e64 v118, v235, -v234
	v_pk_fma_f32 v[120:121], v[72:73], v[118:119], v[80:81] op_sel_hi:[1, 0, 1]
	v_pk_fma_f32 v[122:123], v[70:71], v[118:119], v[78:79] op_sel_hi:[1, 0, 1]
	v_pk_fma_f32 v[112:113], v[112:113], v[234:235], v[120:121] op_sel:[0, 1, 0]
	v_pk_fma_f32 v[110:111], v[110:111], v[234:235], v[122:123] op_sel:[0, 1, 0]
	v_pk_fma_f32 v[120:121], v[56:57], v[118:119], v[64:65] op_sel_hi:[1, 0, 1]
	v_pk_fma_f32 v[122:123], v[54:55], v[118:119], v[62:63] op_sel_hi:[1, 0, 1]
	v_pk_fma_f32 v[120:121], v[108:109], v[234:235], v[120:121] op_sel:[0, 1, 0]
	v_pk_fma_f32 v[108:109], v[106:107], v[234:235], v[122:123] op_sel:[0, 1, 0]
	v_cvt_pk_bf16_f32 v106, v110, v111
	v_cvt_pk_bf16_f32 v107, v112, v113
	s_nop 0
	v_cvt_pk_bf16_f32 v108, v108, v109
	v_cvt_pk_bf16_f32 v109, v120, v121
	global_store_dwordx4 v[116:117], v[106:109], off
	s_nop 1
	v_pk_fma_f32 v[106:107], v[68:69], v[118:119], v[76:77] op_sel_hi:[1, 0, 1]
	v_pk_fma_f32 v[108:109], v[66:67], v[118:119], v[74:75] op_sel_hi:[1, 0, 1]
	v_pk_fma_f32 v[104:105], v[104:105], v[234:235], v[106:107] op_sel:[0, 1, 0]
	v_pk_fma_f32 v[102:103], v[102:103], v[234:235], v[108:109] op_sel:[0, 1, 0]
	v_pk_fma_f32 v[106:107], v[52:53], v[118:119], v[60:61] op_sel_hi:[1, 0, 1]
	v_pk_fma_f32 v[108:109], v[50:51], v[118:119], v[58:59] op_sel_hi:[1, 0, 1]
	v_pk_fma_f32 v[106:107], v[100:101], v[234:235], v[106:107] op_sel:[0, 1, 0]
	v_pk_fma_f32 v[100:101], v[98:99], v[234:235], v[108:109] op_sel:[0, 1, 0]
	v_cvt_pk_bf16_f32 v98, v102, v103
	v_cvt_pk_bf16_f32 v99, v104, v105
	s_nop 0
	v_cvt_pk_bf16_f32 v100, v100, v101
	v_cvt_pk_bf16_f32 v101, v106, v107
	global_store_dwordx4 v[116:117], v[98:101], off offset:256
	s_nop 1
	v_add_u32_e32 v98, 0x80, v162
	v_ashrrev_i32_e32 v99, 31, v98
	v_lshlrev_b64 v[100:101], 12, v[98:99]
	v_lshl_add_u64 v[100:101], s[74:75], 0, v[100:101]
	v_lshl_add_u64 v[100:101], v[100:101], 0, v[164:165]
	v_mul_f32_e64 v102, v237, -v236
	v_pk_fma_f32 v[104:105], v[72:73], v[102:103], v[80:81] op_sel_hi:[1, 0, 1]
	v_pk_fma_f32 v[106:107], v[70:71], v[102:103], v[78:79] op_sel_hi:[1, 0, 1]
	v_pk_fma_f32 v[96:97], v[96:97], v[236:237], v[104:105] op_sel:[0, 1, 0]
	v_pk_fma_f32 v[94:95], v[94:95], v[236:237], v[106:107] op_sel:[0, 1, 0]
	v_pk_fma_f32 v[104:105], v[56:57], v[102:103], v[64:65] op_sel_hi:[1, 0, 1]
	v_pk_fma_f32 v[106:107], v[54:55], v[102:103], v[62:63] op_sel_hi:[1, 0, 1]
	v_pk_fma_f32 v[104:105], v[92:93], v[236:237], v[104:105] op_sel:[0, 1, 0]
	v_pk_fma_f32 v[92:93], v[90:91], v[236:237], v[106:107] op_sel:[0, 1, 0]
	v_cvt_pk_bf16_f32 v90, v94, v95
	v_cvt_pk_bf16_f32 v91, v96, v97
	s_nop 0
	v_cvt_pk_bf16_f32 v92, v92, v93
	v_cvt_pk_bf16_f32 v93, v104, v105
	global_store_dwordx4 v[100:101], v[90:93], off
	s_nop 1
	v_pk_fma_f32 v[90:91], v[68:69], v[102:103], v[76:77] op_sel_hi:[1, 0, 1]
	v_pk_fma_f32 v[92:93], v[66:67], v[102:103], v[74:75] op_sel_hi:[1, 0, 1]
	v_pk_fma_f32 v[88:89], v[88:89], v[236:237], v[90:91] op_sel:[0, 1, 0]
	v_pk_fma_f32 v[86:87], v[86:87], v[236:237], v[92:93] op_sel:[0, 1, 0]
	v_pk_fma_f32 v[90:91], v[52:53], v[102:103], v[60:61] op_sel_hi:[1, 0, 1]
	v_pk_fma_f32 v[92:93], v[50:51], v[102:103], v[58:59] op_sel_hi:[1, 0, 1]
	v_pk_fma_f32 v[90:91], v[84:85], v[236:237], v[90:91] op_sel:[0, 1, 0]
	v_pk_fma_f32 v[84:85], v[82:83], v[236:237], v[92:93] op_sel:[0, 1, 0]
	v_cvt_pk_bf16_f32 v82, v86, v87
	v_cvt_pk_bf16_f32 v83, v88, v89
	s_nop 0
	v_cvt_pk_bf16_f32 v84, v84, v85
	v_cvt_pk_bf16_f32 v85, v90, v91
	global_store_dwordx4 v[100:101], v[82:85], off offset:256
	s_nop 1
	v_add_u32_e32 v82, 0x90, v162
	v_ashrrev_i32_e32 v83, 31, v82
	v_lshlrev_b64 v[84:85], 12, v[82:83]
; __device__ __forceinline__ unsigned cvt_pk_bf16(float lo, float hi) { unsigned r; asm volatile("v_cvt_pk_bf16_f32 %0, %1, %2" : "=v"(r) : "v"(lo), "v"(hi)); return r; }
;     __device__ __forceinline__ void operator()(f32x4 (&acc)[2][2][4][2], const Unit& u, int wr, int wc, int fr, int fq) const {
;     ...
;         for (int ai = 0; ai < 2; ++ai)
; #pragma unroll
;             for (int m = 0; m < 4; ++m) { const int row = row0 + ai * HALF + m * 16; bf16_t* rowp = O + (size_t)row * ldc + col0;
;                 const f32x2 st = *(const f32x2*)(ps + (size_t)row * 2); const float rs = st[1], nm = -st[0] * rs;
; #pragma unroll
;                 for (int bj = 0; bj < 2; ++bj) { const f32x4 v0 = acc[ai][bj][m][0] * rs + (cv[bj][0] * nm + bv[bj][0]), v1 = acc[ai][bj][m][1] * rs + (cv[bj][1] * nm + bv[bj][1]);
;                     u32x4 w; w.x = cvt_pk_bf16(v0[0], v0[1]); w.y = cvt_pk_bf16(v0[2], v0[3]); w.z = cvt_pk_bf16(v1[0], v1[1]); w.w = cvt_pk_bf16(v1[2], v1[3]);
;                     *(u32x4*)(rowp + bj * HALF) = w; } }
	v_lshl_add_u64 v[84:85], s[74:75], 0, v[84:85]
	v_lshl_add_u64 v[84:85], v[84:85], 0, v[164:165]
	v_mul_f32_e64 v86, v239, -v238
	v_pk_fma_f32 v[88:89], v[72:73], v[86:87], v[80:81] op_sel_hi:[1, 0, 1]
	v_pk_fma_f32 v[90:91], v[70:71], v[86:87], v[78:79] op_sel_hi:[1, 0, 1]
	v_pk_fma_f32 v[48:49], v[48:49], v[238:239], v[88:89] op_sel:[0, 1, 0]
	v_pk_fma_f32 v[46:47], v[46:47], v[238:239], v[90:91] op_sel:[0, 1, 0]
	v_pk_fma_f32 v[88:89], v[56:57], v[86:87], v[64:65] op_sel_hi:[1, 0, 1]
	v_pk_fma_f32 v[90:91], v[54:55], v[86:87], v[62:63] op_sel_hi:[1, 0, 1]
	v_pk_fma_f32 v[88:89], v[44:45], v[238:239], v[88:89] op_sel:[0, 1, 0]
	v_pk_fma_f32 v[44:45], v[42:43], v[238:239], v[90:91] op_sel:[0, 1, 0]
	v_cvt_pk_bf16_f32 v42, v46, v47
	v_cvt_pk_bf16_f32 v43, v48, v49
	s_nop 0
	v_cvt_pk_bf16_f32 v44, v44, v45
	v_cvt_pk_bf16_f32 v45, v88, v89
	global_store_dwordx4 v[84:85], v[42:45], off
	s_nop 1
	v_pk_fma_f32 v[42:43], v[68:69], v[86:87], v[76:77] op_sel_hi:[1, 0, 1]
	v_pk_fma_f32 v[44:45], v[66:67], v[86:87], v[74:75] op_sel_hi:[1, 0, 1]
	v_pk_fma_f32 v[40:41], v[40:41], v[238:239], v[42:43] op_sel:[0, 1, 0]
	v_pk_fma_f32 v[38:39], v[38:39], v[238:239], v[44:45] op_sel:[0, 1, 0]
	v_pk_fma_f32 v[42:43], v[52:53], v[86:87], v[60:61] op_sel_hi:[1, 0, 1]
	v_pk_fma_f32 v[44:45], v[50:51], v[86:87], v[58:59] op_sel_hi:[1, 0, 1]
	v_pk_fma_f32 v[42:43], v[36:37], v[238:239], v[42:43] op_sel:[0, 1, 0]
	v_pk_fma_f32 v[36:37], v[34:35], v[238:239], v[44:45] op_sel:[0, 1, 0]
	v_cvt_pk_bf16_f32 v34, v38, v39
	v_cvt_pk_bf16_f32 v35, v40, v41
	s_nop 0
	v_cvt_pk_bf16_f32 v36, v36, v37
	v_cvt_pk_bf16_f32 v37, v42, v43
	global_store_dwordx4 v[84:85], v[34:37], off offset:256
	s_nop 1
	v_add_u32_e32 v34, 0xa0, v162
	v_ashrrev_i32_e32 v35, 31, v34
	v_lshlrev_b64 v[36:37], 12, v[34:35]
	v_lshl_add_u64 v[36:37], s[74:75], 0, v[36:37]
	v_lshl_add_u64 v[36:37], v[36:37], 0, v[164:165]
	v_mul_f32_e64 v38, v241, -v240
	v_pk_fma_f32 v[40:41], v[72:73], v[38:39], v[80:81] op_sel_hi:[1, 0, 1]
	v_pk_fma_f32 v[42:43], v[70:71], v[38:39], v[78:79] op_sel_hi:[1, 0, 1]
	v_pk_fma_f32 v[32:33], v[32:33], v[240:241], v[40:41] op_sel:[0, 1, 0]
	v_pk_fma_f32 v[30:31], v[30:31], v[240:241], v[42:43] op_sel:[0, 1, 0]
	v_pk_fma_f32 v[40:41], v[56:57], v[38:39], v[64:65] op_sel_hi:[1, 0, 1]
	v_pk_fma_f32 v[42:43], v[54:55], v[38:39], v[62:63] op_sel_hi:[1, 0, 1]
	v_pk_fma_f32 v[40:41], v[28:29], v[240:241], v[40:41] op_sel:[0, 1, 0]
	v_pk_fma_f32 v[28:29], v[26:27], v[240:241], v[42:43] op_sel:[0, 1, 0]
	v_cvt_pk_bf16_f32 v26, v30, v31
	v_cvt_pk_bf16_f32 v27, v32, v33
	s_nop 0
	v_cvt_pk_bf16_f32 v28, v28, v29
	v_cvt_pk_bf16_f32 v29, v40, v41
	global_store_dwordx4 v[36:37], v[26:29], off
	s_nop 1
	v_pk_fma_f32 v[26:27], v[68:69], v[38:39], v[76:77] op_sel_hi:[1, 0, 1]
	v_pk_fma_f32 v[28:29], v[66:67], v[38:39], v[74:75] op_sel_hi:[1, 0, 1]
	v_pk_fma_f32 v[24:25], v[24:25], v[240:241], v[26:27] op_sel:[0, 1, 0]
	v_pk_fma_f32 v[22:23], v[22:23], v[240:241], v[28:29] op_sel:[0, 1, 0]
	v_pk_fma_f32 v[26:27], v[52:53], v[38:39], v[60:61] op_sel_hi:[1, 0, 1]
	v_pk_fma_f32 v[28:29], v[50:51], v[38:39], v[58:59] op_sel_hi:[1, 0, 1]
	v_pk_fma_f32 v[26:27], v[20:21], v[240:241], v[26:27] op_sel:[0, 1, 0]
	v_pk_fma_f32 v[20:21], v[18:19], v[240:241], v[28:29] op_sel:[0, 1, 0]
	v_cvt_pk_bf16_f32 v18, v22, v23
	v_cvt_pk_bf16_f32 v19, v24, v25
	s_nop 0
	v_cvt_pk_bf16_f32 v20, v20, v21
	v_cvt_pk_bf16_f32 v21, v26, v27
	global_store_dwordx4 v[36:37], v[18:21], off offset:256
	s_nop 1
	v_add_u32_e32 v18, 0xb0, v162
	v_ashrrev_i32_e32 v19, 31, v18
	v_lshlrev_b64 v[20:21], 12, v[18:19]
	v_lshl_add_u64 v[20:21], s[74:75], 0, v[20:21]
	v_lshl_add_u64 v[20:21], v[20:21], 0, v[164:165]
	v_mul_f32_e64 v22, v197, -v196
	v_pk_fma_f32 v[24:25], v[72:73], v[22:23], v[80:81] op_sel_hi:[1, 0, 1]
	v_pk_fma_f32 v[26:27], v[70:71], v[22:23], v[78:79] op_sel_hi:[1, 0, 1]
	v_pk_fma_f32 v[16:17], v[16:17], v[196:197], v[24:25] op_sel:[0, 1, 0]
	v_pk_fma_f32 v[14:15], v[14:15], v[196:197], v[26:27] op_sel:[0, 1, 0]
	v_pk_fma_f32 v[24:25], v[56:57], v[22:23], v[64:65] op_sel_hi:[1, 0, 1]
	v_pk_fma_f32 v[26:27], v[54:55], v[22:23], v[62:63] op_sel_hi:[1, 0, 1]
	v_pk_fma_f32 v[24:25], v[12:13], v[196:197], v[24:25] op_sel:[0, 1, 0]
	v_pk_fma_f32 v[12:13], v[10:11], v[196:197], v[26:27] op_sel:[0, 1, 0]
	v_cvt_pk_bf16_f32 v10, v14, v15
	v_cvt_pk_bf16_f32 v11, v16, v17
	s_nop 0
	v_cvt_pk_bf16_f32 v12, v12, v13
	v_cvt_pk_bf16_f32 v13, v24, v25
	global_store_dwordx4 v[20:21], v[10:13], off
	s_nop 1
	v_pk_fma_f32 v[10:11], v[68:69], v[22:23], v[76:77] op_sel_hi:[1, 0, 1]
	v_pk_fma_f32 v[12:13], v[66:67], v[22:23], v[74:75] op_sel_hi:[1, 0, 1]
	v_pk_fma_f32 v[8:9], v[8:9], v[196:197], v[10:11] op_sel:[0, 1, 0]
	v_pk_fma_f32 v[6:7], v[6:7], v[196:197], v[12:13] op_sel:[0, 1, 0]
	v_pk_fma_f32 v[10:11], v[52:53], v[22:23], v[60:61] op_sel_hi:[1, 0, 1]
	v_pk_fma_f32 v[12:13], v[50:51], v[22:23], v[58:59] op_sel_hi:[1, 0, 1]
	v_pk_fma_f32 v[10:11], v[4:5], v[196:197], v[10:11] op_sel:[0, 1, 0]
	v_pk_fma_f32 v[4:5], v[2:3], v[196:197], v[12:13] op_sel:[0, 1, 0]
	v_cvt_pk_bf16_f32 v2, v6, v7
	v_cvt_pk_bf16_f32 v3, v8, v9
	s_nop 0
	v_cvt_pk_bf16_f32 v4, v4, v5
	v_cvt_pk_bf16_f32 v5, v10, v11
	global_store_dwordx4 v[20:21], v[2:5], off offset:256
	s_cbranch_vccnz .LBB0_609
	s_andn2_b64 vcc, exec, s[4:5]
	s_cbranch_vccnz .LBB0_608
	s_barrier
	s_branch .LBB0_608
